# attention phase rebuilt on 16x16x32 MFMA (same math and LDS traffic), new LDS swizzles, 8-byte epilogue stores
# baseline (speedup 1.0000x reference)
; __device__ __forceinline__ void attn_phase(int wv, const bf16_t* Q, const bf16_t* Kf, const bf16_t* Vt, const bf16_t* proj, bf16_t* mixed, LAS unsigned char* lds) { LIDS
;     const int tid = tid_l, wid = __builtin_amdgcn_readfirstlane(tid >> 6), lane = tid & 63, r = lane & 31, h = lane >> 5;
;     unsigned koff[3], voff[2];
; #pragma unroll
;     for (int i = 0; i < 3; ++i) { const int j = tid + 512 * i, row = j / 24, cc = (j % 24) ^ ((row >> 1) & 7); koff[i] = (unsigned)(row * (NKF * 2) + cc * 16); }
; #pragma unroll
;     for (int i = 0; i < 2; ++i) { const int j = tid + 512 * i, dv = j >> 3, cc = (j & 7) ^ ((dv >> 1) & 7); voff[i] = (unsigned)dv * (unsigned)(SEQ * 2) + (unsigned)(cc * 16); }
;     const int pr = (r & ~12) | ((r & 4) << 1) | ((r & 8) >> 1);
;     const int kx = (pr >> 1) & 7, kxs = kx >> 1, kx0 = kx & 1;
;     int koffl[4], voffl[4];
; #pragma unroll
;     for (int kl = 0; kl < 4; ++kl) koffl[kl] = pr * 384 + 32 * (kl ^ kxs) + 16 * (h ^ kx0);
;     const int vy = (r >> 1) & 7;
; #pragma unroll
;     for (int c = 0; c < 4; ++c) voffl[c] = r * 128 + 16 * (((c << 1) | h) ^ vy);
;     const unsigned ldsw = (unsigned)wid * 1024u;
;     ...
;     if (wid >= 4) __builtin_amdgcn_s_setprio(1);
;     for (int it = bid_l; it < 256; it += gdim_l) {
;         const int head = it & 7, pi = it >> 3;
;         for (int half = 0; half < 2; ++half) {
;             const int qb = half == 0 ? 63 - pi : pi;
;             const int q0 = qb * 256, qw0 = q0 + 32 * wid, q = qw0 + r, nt = 4 * qb + 4;
;             const char* kbase = (const char*)Kf + head * 192 * 2; const char* vbase = (const char*)Vt + (size_t)head * 128 * SEQ * 2;
;             bf16x8 qf[12];
; #pragma unroll
;             for (int ks = 0; ks < 12; ++ks) qf[ks] = *(const bf16x8*)(Q + (size_t)q * NQ + head * 192 + ks * 16 + h * 8);
.LBB0_92:
	v_writelane_b32 v254, s20, 56
	s_cmpk_gt_i32 s55, 0xff
	s_mov_b32 s81, s17
	v_writelane_b32 v254, s21, 57
	s_cbranch_scc1 .LBB0_111
	s_lshl_b32 s58, s3, 10
	s_add_i32 s58, s58, 16
	v_and_b32_e32 v232, 15, v216
	v_lshrrev_b32_e32 v233, 4, v216
	v_lshl_add_u32 v236, s3, 6, v216
	v_mov_b32_e32 v237, v236
	v_mul_hi_u32 v238, v237, s33
	v_lshrrev_b32_e32 v238, 2, v238
	v_mul_u32_u24_e32 v239, 24, v238
	v_sub_u32_e32 v239, v237, v239
	v_and_b32_e32 v240, 2, v238
	v_lshrrev_b32_e32 v241, 2, v238
	v_and_or_b32 v240, v241, 4, v240
	v_xor_b32_e32 v239, v239, v240
	v_mul_u32_u24_e32 v238, 0xc00, v238
	v_lshl_add_u32 v202, v239, 4, v238
	v_add_u32_e32 v237, 512, v236
	v_mul_hi_u32 v238, v237, s33
	v_lshrrev_b32_e32 v238, 2, v238
	v_mul_u32_u24_e32 v239, 24, v238
	v_sub_u32_e32 v239, v237, v239
	v_and_b32_e32 v240, 2, v238
	v_lshrrev_b32_e32 v241, 2, v238
	v_and_or_b32 v240, v241, 4, v240
	v_xor_b32_e32 v239, v239, v240
	v_mul_u32_u24_e32 v238, 0xc00, v238
	v_lshl_add_u32 v203, v239, 4, v238
	v_add_u32_e32 v237, 1024, v236
	v_mul_hi_u32 v238, v237, s33
	v_lshrrev_b32_e32 v238, 2, v238
	v_mul_u32_u24_e32 v239, 24, v238
	v_sub_u32_e32 v239, v237, v239
	v_and_b32_e32 v240, 2, v238
	v_lshrrev_b32_e32 v241, 2, v238
	v_and_or_b32 v240, v241, 4, v240
	v_xor_b32_e32 v239, v239, v240
	v_mul_u32_u24_e32 v238, 0xc00, v238
	v_lshl_add_u32 v204, v239, 4, v238
	v_mov_b32_e32 v237, v236
	v_lshrrev_b32_e32 v238, 3, v237
	v_and_b32_e32 v239, 7, v237
	v_and_b32_e32 v240, 2, v238
	v_lshrrev_b32_e32 v241, 1, v238
	v_and_or_b32 v240, v241, 4, v240
	v_xor_b32_e32 v239, v239, v240
	v_lshlrev_b32_e32 v238, 15, v238
	v_lshl_add_u32 v205, v239, 4, v238
	v_add_u32_e32 v237, 512, v236
	v_lshrrev_b32_e32 v238, 3, v237
	v_and_b32_e32 v239, 7, v237
	v_and_b32_e32 v240, 2, v238
	v_lshrrev_b32_e32 v241, 1, v238
	v_and_or_b32 v240, v241, 4, v240
	v_xor_b32_e32 v239, v239, v240
	v_lshlrev_b32_e32 v238, 15, v238
	v_lshl_add_u32 v206, v239, 4, v238
	v_and_b32_e32 v237, 2, v232
	v_xor_b32_e32 v237, v233, v237
	v_lshlrev_b32_e32 v237, 4, v237
	v_bfe_u32 v238, v232, 3, 1
	v_lshlrev_b32_e32 v238, 6, v238
	v_lshrrev_b32_e32 v239, 2, v232
	v_and_b32_e32 v240, 3, v232
	v_lshl_add_u32 v239, v239, 3, v240
	v_mul_u32_u24_e32 v239, 0x180, v239
	v_add_u32_e32 v239, v239, v237
	v_add_u32_e32 v207, v239, v238
	v_sub_u32_e32 v208, v239, v238
	v_lshl_add_u32 v239, v232, 7, v237
	v_add_u32_e32 v209, v239, v238
	v_sub_u32_e32 v240, 64, v238
	v_add_u32_e32 v210, v239, v240
	v_add_u32_e32 v211, 0x8000, v209
	v_add_u32_e32 v212, 0x8000, v210
	v_readlane_b32 s4, v254, 38
	v_readlane_b32 s5, v254, 39
	s_load_dword s57, s[4:5], 0x0
	s_waitcnt lgkmcnt(0)
.La3_item:
	s_and_b32 s8, s55, 7
	s_ashr_i32 s59, s55, 3
	s_mul_i32 s0, s8, 0x180
	v_readlane_b32 s4, v254, 42
	v_readlane_b32 s5, v254, 43
	s_add_u32 s4, s4, s0
	s_addc_u32 s5, s5, 0
	v_readlane_b32 s10, v254, 44
	v_readlane_b32 s11, v254, 45
	s_add_u32 s10, s10, s0
	s_addc_u32 s11, s11, 0
	v_readlane_b32 s6, v253, 8
	v_readlane_b32 s7, v253, 9
	s_lshl_b32 s0, s8, 22
	s_add_u32 s6, s6, s0
	s_addc_u32 s7, s7, 0
	s_lshl_b32 s0, s8, 8
	v_readlane_b32 s20, v254, 50
	v_readlane_b32 s21, v254, 51
	s_add_u32 s12, s20, s0
	s_addc_u32 s13, s21, 0
	s_add_u32 s12, s12, 0x4000680
	s_addc_u32 s13, s13, 0
	s_add_u32 s20, s20, s0
	s_addc_u32 s21, s21, 0
	s_mov_b32 s68, 0
.La3_unit:
	s_sub_i32 s9, 63, s59
	s_cmp_eq_u32 s68, 0
	s_cselect_b32 s9, s9, s59
	s_lshl_b32 s16, s9, 8
	s_lshl_b32 s0, s3, 5
	s_add_i32 s16, s16, s0
	s_lshl_b32 s17, s9, 2
	s_add_i32 s17, s17, 4
	s_lshr_b32 s18, s16, 6
	v_add_u32_e32 v236, s16, v232
	v_lshlrev_b32_e32 v237, 3, v233
	v_sub_u32_e32 v231, v236, v237
	v_mul_u32_u24_e32 v238, 0xc00, v236
	v_lshl_add_u32 v234, v233, 4, v238
	v_add_u32_e32 v235, 0xc000, v234
	v_lshlrev_b32_e32 v238, 13, v236
	v_lshl_add_u32 v244, v233, 3, v238
	v_add_u32_e32 v245, 0x20000, v244
	v_lshlrev_b32_e32 v238, 12, v236
	v_lshl_add_u32 v246, v233, 3, v238
	v_add_u32_e32 v247, 0x10000, v246
	global_load_dwordx4 v[128:131], v234, s[10:11] offset:0
	global_load_dwordx4 v[132:135], v234, s[10:11] offset:64
	global_load_dwordx4 v[136:139], v234, s[10:11] offset:128
	global_load_dwordx4 v[140:143], v234, s[10:11] offset:192
	global_load_dwordx4 v[144:147], v234, s[10:11] offset:256
	global_load_dwordx4 v[148:151], v234, s[10:11] offset:320
	global_load_dwordx4 v[152:155], v235, s[10:11] offset:0
	global_load_dwordx4 v[156:159], v235, s[10:11] offset:64
	global_load_dwordx4 v[160:163], v235, s[10:11] offset:128
	global_load_dwordx4 v[164:167], v235, s[10:11] offset:192
	global_load_dwordx4 v[168:171], v235, s[10:11] offset:256
	global_load_dwordx4 v[172:175], v235, s[10:11] offset:320
	s_barrier
; #define LAS __attribute__((address_space(3)))
; #define LGK(n, f) asm volatile("s_waitcnt lgkmcnt(%1)" : "+v"(f) : "n"(n))
; #define ATT_KRD(i) DSR(fr_[(i) & 3], kad[((i) >> 1) & 3], ((i) & 1) * (32 * 384) + ((i) >> 3) * 128)
; __device__ __forceinline__ void attn_phase(int wv, const bf16_t* Q, const bf16_t* Kf, const bf16_t* Vt, const bf16_t* proj, bf16_t* mixed, LAS unsigned char* lds) { LIDS
;     ...
;             float zf = 0.f; asm volatile("" : "+v"(zf));
;             f32x16 o[4];
; #pragma unroll
;             for (int b = 0; b < 4; ++b)
; #pragma unroll
;                 for (int j = 0; j < 16; ++j) o[b][j] = zf;
;             float mrun = -1e30f, lsum = 0.f;
;             asm volatile("" ::: "memory"); __builtin_amdgcn_s_barrier(); asm volatile("" ::: "memory");
;             ATT_ISSUE(0, 0);
;             for (int t = 0; t < nt; ++t) {
;                 const int b = t & 1;
;                 asm volatile("s_waitcnt vmcnt(0)" ::: "memory"); __builtin_amdgcn_s_barrier(); asm volatile("" ::: "memory");
;                 if (t + 1 < nt) ATT_ISSUE(t + 1, b ^ 1);
;                 if (64 * t <= qw0 + 31) {
;                     LAS unsigned char* kb_ = lds + b * ATT_STAGE; LAS unsigned char* vb_ = kb_ + ATT_KB;
;                     f32x16 s[2];
; #pragma unroll
;                     for (int kb = 0; kb < 2; ++kb)
; #pragma unroll
;                         for (int j = 0; j < 16; ++j) s[kb][j] = zf;
;                     unsigned kad[4];
; #pragma unroll
;                     for (int kl = 0; kl < 4; ++kl) kad[kl] = (unsigned)(size_t)kb_ + (unsigned)koffl[kl];
;                     bf16x8 fr_[4];
;     ...
;                     ATT_KRD(0); ATT_KRD(1); ATT_KRD(2); ATT_KRD(3);
; #pragma unroll
;                     for (int i = 0; i < 24; ++i) {
;                         LGK(i < 21 ? 3 : 23 - i, fr_[i & 3]);
;                         s[i & 1] = __builtin_amdgcn_mfma_f32_32x32x16_bf16(fr_[i & 3], qf[i >> 1], s[i & 1], 0, 0, 0);
;                         if (i + 4 < 24) ATT_KRD(i + 4);
;                     }
	s_mov_b64 s[62:63], s[4:5]
	s_mov_b64 s[72:73], s[6:7]
	s_mov_b32 m0, s58
	s_nop 0
	global_load_lds_dwordx4 v202, s[62:63]
	s_add_i32 m0, s58, 0x2000
	s_nop 0
	global_load_lds_dwordx4 v203, s[62:63]
	s_add_i32 m0, s58, 0x4000
	s_nop 0
	global_load_lds_dwordx4 v204, s[62:63]
	s_add_i32 m0, s58, 0x6000
	s_nop 0
	global_load_lds_dwordx4 v205, s[72:73]
	s_add_i32 m0, s58, 0x8000
	s_nop 0
	global_load_lds_dwordx4 v206, s[72:73]
	s_add_u32 s62, s62, 0x30000
	s_addc_u32 s63, s63, 0
	s_add_i32 m0, s58, 0xa000
	s_nop 0
	global_load_lds_dwordx4 v202, s[62:63]
	s_add_i32 m0, s58, 0xc000
	s_nop 0
	global_load_lds_dwordx4 v203, s[62:63]
	s_add_i32 m0, s58, 0xe000
	s_nop 0
	global_load_lds_dwordx4 v204, s[62:63]
	s_add_u32 s62, s62, 0x30000
	s_addc_u32 s63, s63, 0
	s_add_u32 s72, s72, 0x80
	s_addc_u32 s73, s73, 0
	v_mov_b32_e32 v0, 0
	v_mov_b32_e32 v1, 0
	v_mov_b32_e32 v2, 0
	v_mov_b32_e32 v3, 0
	v_mov_b32_e32 v4, 0
	v_mov_b32_e32 v5, 0
	v_mov_b32_e32 v6, 0
	v_mov_b32_e32 v7, 0
	v_mov_b32_e32 v8, 0
	v_mov_b32_e32 v9, 0
	v_mov_b32_e32 v10, 0
	v_mov_b32_e32 v11, 0
	v_mov_b32_e32 v12, 0
	v_mov_b32_e32 v13, 0
	v_mov_b32_e32 v14, 0
	v_mov_b32_e32 v15, 0
	v_mov_b32_e32 v16, 0
	v_mov_b32_e32 v17, 0
	v_mov_b32_e32 v18, 0
	v_mov_b32_e32 v19, 0
	v_mov_b32_e32 v20, 0
	v_mov_b32_e32 v21, 0
	v_mov_b32_e32 v22, 0
	v_mov_b32_e32 v23, 0
	v_mov_b32_e32 v24, 0
	v_mov_b32_e32 v25, 0
	v_mov_b32_e32 v26, 0
	v_mov_b32_e32 v27, 0
	v_mov_b32_e32 v28, 0
	v_mov_b32_e32 v29, 0
	v_mov_b32_e32 v30, 0
	v_mov_b32_e32 v31, 0
	v_mov_b32_e32 v32, 0
	v_mov_b32_e32 v33, 0
	v_mov_b32_e32 v34, 0
	v_mov_b32_e32 v35, 0
	v_mov_b32_e32 v36, 0
	v_mov_b32_e32 v37, 0
	v_mov_b32_e32 v38, 0
	v_mov_b32_e32 v39, 0
	v_mov_b32_e32 v40, 0
	v_mov_b32_e32 v41, 0
	v_mov_b32_e32 v42, 0
	v_mov_b32_e32 v43, 0
	v_mov_b32_e32 v44, 0
	v_mov_b32_e32 v45, 0
	v_mov_b32_e32 v46, 0
	v_mov_b32_e32 v47, 0
	v_mov_b32_e32 v48, 0
	v_mov_b32_e32 v49, 0
	v_mov_b32_e32 v50, 0
	v_mov_b32_e32 v51, 0
	v_mov_b32_e32 v52, 0
	v_mov_b32_e32 v53, 0
	v_mov_b32_e32 v54, 0
	v_mov_b32_e32 v55, 0
	v_mov_b32_e32 v56, 0
	v_mov_b32_e32 v57, 0
	v_mov_b32_e32 v58, 0
	v_mov_b32_e32 v59, 0
	v_mov_b32_e32 v60, 0
	v_mov_b32_e32 v61, 0
	v_mov_b32_e32 v62, 0
	v_mov_b32_e32 v63, 0
	v_mov_b32_e32 v226, 0
	v_mov_b32_e32 v228, v215
	v_mov_b32_e32 v194, 0
	v_mov_b32_e32 v195, 0
	v_mov_b32_e32 v196, 0
	v_mov_b32_e32 v197, 0
	v_mov_b32_e32 v227, 0
	v_mov_b32_e32 v229, v215
	v_mov_b32_e32 v198, 0
	v_mov_b32_e32 v199, 0
	v_mov_b32_e32 v200, 0
	v_mov_b32_e32 v201, 0
	v_mov_b32_e32 v230, v215
	s_mov_b32 s19, 0
	s_waitcnt vmcnt(0)
	s_barrier
	ds_read_b128 v[178:181], v207 offset:16
	ds_read_b128 v[182:185], v207 offset:1552
	ds_read_b128 v[186:189], v207 offset:12304
	ds_read_b128 v[190:193], v207 offset:13840
	s_waitcnt lgkmcnt(3)
	v_mfma_f32_16x16x32_bf16 v[64:67], v[178:181], v[128:131], v[194:197]
	v_mfma_f32_16x16x32_bf16 v[68:71], v[178:181], v[152:155], v[198:201]
	ds_read_b128 v[178:181], v208 offset:80
	s_waitcnt lgkmcnt(3)
	v_mfma_f32_16x16x32_bf16 v[72:75], v[182:185], v[128:131], v[194:197]
	v_mfma_f32_16x16x32_bf16 v[76:79], v[182:185], v[152:155], v[198:201]
	ds_read_b128 v[182:185], v208 offset:1616
	s_waitcnt lgkmcnt(3)
	v_mfma_f32_16x16x32_bf16 v[80:83], v[186:189], v[128:131], v[194:197]
	v_mfma_f32_16x16x32_bf16 v[84:87], v[186:189], v[152:155], v[198:201]
	ds_read_b128 v[186:189], v208 offset:12368
	s_waitcnt lgkmcnt(3)
	v_mfma_f32_16x16x32_bf16 v[88:91], v[190:193], v[128:131], v[194:197]
	v_mfma_f32_16x16x32_bf16 v[92:95], v[190:193], v[152:155], v[198:201]
	ds_read_b128 v[190:193], v208 offset:13904
	s_waitcnt lgkmcnt(3)
	v_mfma_f32_16x16x32_bf16 v[64:67], v[178:181], v[132:135], v[64:67]
	v_mfma_f32_16x16x32_bf16 v[68:71], v[178:181], v[156:159], v[68:71]
	ds_read_b128 v[178:181], v207 offset:144
	s_waitcnt lgkmcnt(3)
	v_mfma_f32_16x16x32_bf16 v[72:75], v[182:185], v[132:135], v[72:75]
	v_mfma_f32_16x16x32_bf16 v[76:79], v[182:185], v[156:159], v[76:79]
	ds_read_b128 v[182:185], v207 offset:1680
	s_waitcnt lgkmcnt(3)
	v_mfma_f32_16x16x32_bf16 v[80:83], v[186:189], v[132:135], v[80:83]
	v_mfma_f32_16x16x32_bf16 v[84:87], v[186:189], v[156:159], v[84:87]
	ds_read_b128 v[186:189], v207 offset:12432
	s_waitcnt lgkmcnt(3)
	v_mfma_f32_16x16x32_bf16 v[88:91], v[190:193], v[132:135], v[88:91]
	v_mfma_f32_16x16x32_bf16 v[92:95], v[190:193], v[156:159], v[92:95]
	ds_read_b128 v[190:193], v207 offset:13968
	s_waitcnt lgkmcnt(3)
	v_mfma_f32_16x16x32_bf16 v[64:67], v[178:181], v[136:139], v[64:67]
	v_mfma_f32_16x16x32_bf16 v[68:71], v[178:181], v[160:163], v[68:71]
	ds_read_b128 v[178:181], v208 offset:208
	s_waitcnt lgkmcnt(3)
	v_mfma_f32_16x16x32_bf16 v[72:75], v[182:185], v[136:139], v[72:75]
	v_mfma_f32_16x16x32_bf16 v[76:79], v[182:185], v[160:163], v[76:79]
	ds_read_b128 v[182:185], v208 offset:1744
	s_waitcnt lgkmcnt(3)
	v_mfma_f32_16x16x32_bf16 v[80:83], v[186:189], v[136:139], v[80:83]
	v_mfma_f32_16x16x32_bf16 v[84:87], v[186:189], v[160:163], v[84:87]
	ds_read_b128 v[186:189], v208 offset:12496
	s_waitcnt lgkmcnt(3)
	v_mfma_f32_16x16x32_bf16 v[88:91], v[190:193], v[136:139], v[88:91]
	v_mfma_f32_16x16x32_bf16 v[92:95], v[190:193], v[160:163], v[92:95]
	ds_read_b128 v[190:193], v208 offset:14032
	s_waitcnt lgkmcnt(3)
	v_mfma_f32_16x16x32_bf16 v[64:67], v[178:181], v[140:143], v[64:67]
	v_mfma_f32_16x16x32_bf16 v[68:71], v[178:181], v[164:167], v[68:71]
	ds_read_b128 v[178:181], v207 offset:272
	s_waitcnt lgkmcnt(3)
	v_mfma_f32_16x16x32_bf16 v[72:75], v[182:185], v[140:143], v[72:75]
	v_mfma_f32_16x16x32_bf16 v[76:79], v[182:185], v[164:167], v[76:79]
	ds_read_b128 v[182:185], v207 offset:1808
	s_waitcnt lgkmcnt(3)
; #define LGK(n, f) asm volatile("s_waitcnt lgkmcnt(%1)" : "+v"(f) : "n"(n))
; #define ATT_KRD(i) DSR(fr_[(i) & 3], kad[((i) >> 1) & 3], ((i) & 1) * (32 * 384) + ((i) >> 3) * 128)
; #define ATT_VRD(j) DSR(fr_[(j) & 3], vad[(j) >> 2], ((j) & 3) * 4096)
; __device__ __forceinline__ void attn_phase(int wv, const bf16_t* Q, const bf16_t* Kf, const bf16_t* Vt, const bf16_t* proj, bf16_t* mixed, LAS unsigned char* lds) { LIDS
;     ...
;                     ATT_KRD(0); ATT_KRD(1); ATT_KRD(2); ATT_KRD(3);
; #pragma unroll
;                     for (int i = 0; i < 24; ++i) {
;                         LGK(i < 21 ? 3 : 23 - i, fr_[i & 3]);
;                         s[i & 1] = __builtin_amdgcn_mfma_f32_32x32x16_bf16(fr_[i & 3], qf[i >> 1], s[i & 1], 0, 0, 0);
;                         if (i + 4 < 24) ATT_KRD(i + 4);
;                     }
;     ...
;                     unsigned vad[4];
; #pragma unroll
;                     for (int c = 0; c < 4; ++c) vad[c] = (unsigned)(size_t)vb_ + (unsigned)voffl[c];
;     ...
;                     ATT_VRD(0); ATT_VRD(1); ATT_VRD(2); ATT_VRD(3);
;                     if (64 * t + 63 > qw0) {
; #pragma unroll
;                         for (int kb = 0; kb < 2; ++kb)
; #pragma unroll
;                             for (int j = 0; j < 16; ++j) { const int key = 64 * t + 32 * kb + 16 * (j >> 3) + 8 * h + (j & 7); if (key > q) s[kb][j] = -1e30f; }
;                     }
;                     float mx = -1e30f;
; #pragma unroll
;                     for (int kb = 0; kb < 2; ++kb)
; #pragma unroll
;                         for (int j = 0; j < 16; ++j) mx = fmaxf(mx, s[kb][j]);
;                     mx = fmaxf(mx, __shfl_xor(mx, 32));
;                     if (__builtin_amdgcn_ballot_w64(mx > mrun + 8.0f) != 0ull) {
	v_mfma_f32_16x16x32_bf16 v[80:83], v[186:189], v[140:143], v[80:83]
	v_mfma_f32_16x16x32_bf16 v[84:87], v[186:189], v[164:167], v[84:87]
	ds_read_b128 v[186:189], v207 offset:12560
	s_waitcnt lgkmcnt(3)
	v_mfma_f32_16x16x32_bf16 v[88:91], v[190:193], v[140:143], v[88:91]
	v_mfma_f32_16x16x32_bf16 v[92:95], v[190:193], v[164:167], v[92:95]
	ds_read_b128 v[190:193], v207 offset:14096
	s_waitcnt lgkmcnt(3)
	v_mfma_f32_16x16x32_bf16 v[64:67], v[178:181], v[144:147], v[64:67]
	v_mfma_f32_16x16x32_bf16 v[68:71], v[178:181], v[168:171], v[68:71]
	ds_read_b128 v[178:181], v208 offset:336
	s_waitcnt lgkmcnt(3)
	v_mfma_f32_16x16x32_bf16 v[72:75], v[182:185], v[144:147], v[72:75]
	v_mfma_f32_16x16x32_bf16 v[76:79], v[182:185], v[168:171], v[76:79]
	ds_read_b128 v[182:185], v208 offset:1872
	s_waitcnt lgkmcnt(3)
	v_mfma_f32_16x16x32_bf16 v[80:83], v[186:189], v[144:147], v[80:83]
	v_mfma_f32_16x16x32_bf16 v[84:87], v[186:189], v[168:171], v[84:87]
	ds_read_b128 v[186:189], v208 offset:12624
	s_waitcnt lgkmcnt(3)
	v_mfma_f32_16x16x32_bf16 v[88:91], v[190:193], v[144:147], v[88:91]
	v_mfma_f32_16x16x32_bf16 v[92:95], v[190:193], v[168:171], v[92:95]
	ds_read_b128 v[190:193], v208 offset:14160
	s_waitcnt lgkmcnt(3)
	v_mfma_f32_16x16x32_bf16 v[64:67], v[178:181], v[148:151], v[64:67]
	v_mfma_f32_16x16x32_bf16 v[68:71], v[178:181], v[172:175], v[68:71]
	s_waitcnt lgkmcnt(2)
	v_mfma_f32_16x16x32_bf16 v[72:75], v[182:185], v[148:151], v[72:75]
	v_mfma_f32_16x16x32_bf16 v[76:79], v[182:185], v[172:175], v[76:79]
	s_waitcnt lgkmcnt(1)
	v_mfma_f32_16x16x32_bf16 v[80:83], v[186:189], v[148:151], v[80:83]
	v_mfma_f32_16x16x32_bf16 v[84:87], v[186:189], v[172:175], v[84:87]
	s_waitcnt lgkmcnt(0)
	v_mfma_f32_16x16x32_bf16 v[88:91], v[190:193], v[148:151], v[88:91]
	v_mfma_f32_16x16x32_bf16 v[92:95], v[190:193], v[172:175], v[92:95]
	s_nop 9
	s_cmp_lg_u32 s18, 0
	s_cbranch_scc1 .La3_nomask1
	s_mov_b32 s23, 0
	v_subrev_u32_e32 v221, s23, v231
	v_cmp_le_i32_e32 vcc, 0, v221
	s_nop 1
	v_cndmask_b32_e32 v64, v215, v64, vcc
	v_cmp_le_i32_e32 vcc, 1, v221
	s_nop 1
	v_cndmask_b32_e32 v65, v215, v65, vcc
	v_cmp_le_i32_e32 vcc, 2, v221
	s_nop 1
	v_cndmask_b32_e32 v66, v215, v66, vcc
	v_cmp_le_i32_e32 vcc, 3, v221
	s_nop 1
	v_cndmask_b32_e32 v67, v215, v67, vcc
	v_cmp_le_i32_e32 vcc, -16, v221
	s_nop 1
	v_cndmask_b32_e32 v68, v215, v68, vcc
	v_cmp_le_i32_e32 vcc, -15, v221
	s_nop 1
	v_cndmask_b32_e32 v69, v215, v69, vcc
	v_cmp_le_i32_e32 vcc, -14, v221
	s_nop 1
	v_cndmask_b32_e32 v70, v215, v70, vcc
	v_cmp_le_i32_e32 vcc, -13, v221
	s_nop 1
	v_cndmask_b32_e32 v71, v215, v71, vcc
	v_cmp_le_i32_e32 vcc, 4, v221
	s_nop 1
	v_cndmask_b32_e32 v72, v215, v72, vcc
	v_cmp_le_i32_e32 vcc, 5, v221
	s_nop 1
	v_cndmask_b32_e32 v73, v215, v73, vcc
	v_cmp_le_i32_e32 vcc, 6, v221
	s_nop 1
	v_cndmask_b32_e32 v74, v215, v74, vcc
	v_cmp_le_i32_e32 vcc, 7, v221
	s_nop 1
	v_cndmask_b32_e32 v75, v215, v75, vcc
	v_cmp_le_i32_e32 vcc, -12, v221
	s_nop 1
	v_cndmask_b32_e32 v76, v215, v76, vcc
	v_cmp_le_i32_e32 vcc, -11, v221
	s_nop 1
	v_cndmask_b32_e32 v77, v215, v77, vcc
	v_cmp_le_i32_e32 vcc, -10, v221
	s_nop 1
	v_cndmask_b32_e32 v78, v215, v78, vcc
	v_cmp_le_i32_e32 vcc, -9, v221
	s_nop 1
	v_cndmask_b32_e32 v79, v215, v79, vcc
	v_cmp_le_i32_e32 vcc, 32, v221
	s_nop 1
	v_cndmask_b32_e32 v80, v215, v80, vcc
	v_cmp_le_i32_e32 vcc, 33, v221
	s_nop 1
	v_cndmask_b32_e32 v81, v215, v81, vcc
	v_cmp_le_i32_e32 vcc, 34, v221
	s_nop 1
	v_cndmask_b32_e32 v82, v215, v82, vcc
	v_cmp_le_i32_e32 vcc, 35, v221
	s_nop 1
	v_cndmask_b32_e32 v83, v215, v83, vcc
	v_cmp_le_i32_e32 vcc, 16, v221
	s_nop 1
	v_cndmask_b32_e32 v84, v215, v84, vcc
	v_cmp_le_i32_e32 vcc, 17, v221
	s_nop 1
	v_cndmask_b32_e32 v85, v215, v85, vcc
	v_cmp_le_i32_e32 vcc, 18, v221
	s_nop 1
	v_cndmask_b32_e32 v86, v215, v86, vcc
	v_cmp_le_i32_e32 vcc, 19, v221
	s_nop 1
	v_cndmask_b32_e32 v87, v215, v87, vcc
	v_cmp_le_i32_e32 vcc, 36, v221
	s_nop 1
	v_cndmask_b32_e32 v88, v215, v88, vcc
	v_cmp_le_i32_e32 vcc, 37, v221
	s_nop 1
	v_cndmask_b32_e32 v89, v215, v89, vcc
	v_cmp_le_i32_e32 vcc, 38, v221
	s_nop 1
	v_cndmask_b32_e32 v90, v215, v90, vcc
	v_cmp_le_i32_e32 vcc, 39, v221
	s_nop 1
	v_cndmask_b32_e32 v91, v215, v91, vcc
	v_cmp_le_i32_e32 vcc, 20, v221
	s_nop 1
	v_cndmask_b32_e32 v92, v215, v92, vcc
	v_cmp_le_i32_e32 vcc, 21, v221
	s_nop 1
	v_cndmask_b32_e32 v93, v215, v93, vcc
	v_cmp_le_i32_e32 vcc, 22, v221
	s_nop 1
	v_cndmask_b32_e32 v94, v215, v94, vcc
	v_cmp_le_i32_e32 vcc, 23, v221
	s_nop 1
	v_cndmask_b32_e32 v95, v215, v95, vcc
.La3_nomask1:
	v_max3_f32 v218, v64, v65, v66
	v_max3_f32 v218, v218, v67, v72
	v_max3_f32 v218, v218, v73, v74
	v_max3_f32 v218, v218, v75, v80
	v_max3_f32 v218, v218, v81, v82
	v_max3_f32 v218, v218, v83, v88
	v_max3_f32 v218, v218, v89, v90
	v_max_f32_e32 v218, v218, v91
	v_max3_f32 v219, v68, v69, v70
	v_max3_f32 v219, v219, v71, v76
	v_max3_f32 v219, v219, v77, v78
	v_max3_f32 v219, v219, v79, v84
	v_max3_f32 v219, v219, v85, v86
	v_max3_f32 v219, v219, v87, v92
	v_max3_f32 v219, v219, v93, v94
	v_max_f32_e32 v219, v219, v95
	s_nop 1
	v_permlane16_swap_b32_e32 v218, v219
	v_max_f32_e32 v218, v218, v219
	v_mov_b32_e32 v219, v218
	s_nop 1
	v_permlane32_swap_b32_e32 v218, v219
	v_max_f32_e32 v218, v218, v219
	v_mov_b32_e32 v219, v218
	s_nop 1
	v_permlane16_swap_b32_e32 v218, v219
	v_max_f32_e32 v220, v218, v219
	v_cmp_gt_f32_e32 vcc, v220, v230
	s_cbranch_vccnz .La3_rareP
; #define LAS __attribute__((address_space(3)))
; __device__ __forceinline__ unsigned cvt_pk_bf16(float lo, float hi) { unsigned r; asm volatile("v_cvt_pk_bf16_f32 %0, %1, %2" : "=v"(r) : "v"(lo), "v"(hi)); return r; }
; __device__ __forceinline__ float fast_exp2(float x) { return __builtin_amdgcn_exp2f(x); }
; #define LGK(n, f) asm volatile("s_waitcnt lgkmcnt(%1)" : "+v"(f) : "n"(n))
; __device__ __forceinline__ void attn_phase(int wv, const bf16_t* Q, const bf16_t* Kf, const bf16_t* Vt, const bf16_t* proj, bf16_t* mixed, LAS unsigned char* lds) { LIDS
;     ...
;             for (int t = 0; t < nt; ++t) {
;                 const int b = t & 1;
;                 asm volatile("s_waitcnt vmcnt(0)" ::: "memory"); __builtin_amdgcn_s_barrier(); asm volatile("" ::: "memory");
;                 if (t + 1 < nt) ATT_ISSUE(t + 1, b ^ 1);
;                 if (64 * t <= qw0 + 31) {
;                     LAS unsigned char* kb_ = lds + b * ATT_STAGE; LAS unsigned char* vb_ = kb_ + ATT_KB;
;                     f32x16 s[2];
; #pragma unroll
;                     for (int kb = 0; kb < 2; ++kb)
; #pragma unroll
;                         for (int j = 0; j < 16; ++j) s[kb][j] = zf;
;                     unsigned kad[4];
; #pragma unroll
;                     for (int kl = 0; kl < 4; ++kl) kad[kl] = (unsigned)(size_t)kb_ + (unsigned)koffl[kl];
;                     bf16x8 fr_[4];
;     ...
;                     ATT_KRD(0); ATT_KRD(1); ATT_KRD(2); ATT_KRD(3);
; #pragma unroll
;                     for (int i = 0; i < 24; ++i) {
;                         LGK(i < 21 ? 3 : 23 - i, fr_[i & 3]);
;                         s[i & 1] = __builtin_amdgcn_mfma_f32_32x32x16_bf16(fr_[i & 3], qf[i >> 1], s[i & 1], 0, 0, 0);
;                         if (i + 4 < 24) ATT_KRD(i + 4);
;     ...
;                     float ps = 0.f;
; #pragma unroll
;                     for (int kb = 0; kb < 2; ++kb)
; #pragma unroll
;                         for (int j = 0; j < 16; ++j) { s[kb][j] = fast_exp2(s[kb][j] - mrun); ps += s[kb][j]; }
;                     lsum += ps;
; #pragma unroll
;                     for (int c = 0; c < 4; ++c) {
;                         const int kb = c >> 1, sx = c & 1;
;                         u32x4 pw;
; #pragma unroll
;                         for (int j = 0; j < 4; ++j) pw[j] = cvt_pk_bf16(s[kb][8 * sx + 2 * j], s[kb][8 * sx + 2 * j + 1]);
.La3_loop0:
.La3_top0:
	s_waitcnt vmcnt(0)
	s_barrier
	s_add_i32 s22, s19, 2
	s_add_i32 s24, s19, 1
	s_cmp_gt_i32 s19, s18
	s_cbranch_scc1 .La3_idle0
	s_cmp_eq_u32 s19, s18
	s_cbranch_scc1 .La3_drain0
	ds_read_b128 v[178:181], v207 offset:40976
	ds_read_b128 v[182:185], v207 offset:42512
	ds_read_b128 v[186:189], v207 offset:53264
	ds_read_b128 v[190:193], v207 offset:54800
	s_waitcnt lgkmcnt(2)
	v_mfma_f32_16x16x32_bf16 v[96:99], v[178:181], v[128:131], v[194:197]
	v_exp_f32_e32 v64, v64
	v_mfma_f32_16x16x32_bf16 v[100:103], v[178:181], v[152:155], v[198:201]
	ds_read_b128 v[178:181], v208 offset:41040
	v_exp_f32_e32 v65, v65
	v_mfma_f32_16x16x32_bf16 v[104:107], v[182:185], v[128:131], v[194:197]
	v_add_f32_e32 v224, v64, v65
	v_cvt_pk_bf16_f32 v64, v64, v65
	v_mfma_f32_16x16x32_bf16 v[108:111], v[182:185], v[152:155], v[198:201]
	ds_read_b128 v[182:185], v208 offset:42576
	v_exp_f32_e32 v66, v66
	s_waitcnt lgkmcnt(2)
	v_mfma_f32_16x16x32_bf16 v[112:115], v[186:189], v[128:131], v[194:197]
	v_exp_f32_e32 v67, v67
	v_mfma_f32_16x16x32_bf16 v[116:119], v[186:189], v[152:155], v[198:201]
	ds_read_b128 v[186:189], v208 offset:53328
	v_add_f32_e32 v224, v224, v66
	v_add_f32_e32 v224, v224, v67
	s_cmp_ge_i32 s22, s17
	s_cbranch_scc1 .La3_nd3
	s_mov_b32 m0, s58
	s_nop 0
	global_load_lds_dwordx4 v202, s[62:63]
.La3_nd3:
	v_mfma_f32_16x16x32_bf16 v[120:123], v[190:193], v[128:131], v[194:197]
	v_cvt_pk_bf16_f32 v65, v66, v67
	v_mfma_f32_16x16x32_bf16 v[124:127], v[190:193], v[152:155], v[198:201]
	ds_read_b128 v[190:193], v208 offset:54864
	v_exp_f32_e32 v72, v72
	s_waitcnt lgkmcnt(2)
	v_mfma_f32_16x16x32_bf16 v[96:99], v[178:181], v[132:135], v[96:99]
	v_exp_f32_e32 v73, v73
	v_mfma_f32_16x16x32_bf16 v[100:103], v[178:181], v[156:159], v[100:103]
	ds_read_b128 v[178:181], v207 offset:41104
	v_add_f32_e32 v224, v224, v72
	v_add_f32_e32 v224, v224, v73
	v_mfma_f32_16x16x32_bf16 v[104:107], v[182:185], v[132:135], v[104:107]
	v_cvt_pk_bf16_f32 v66, v72, v73
	v_mfma_f32_16x16x32_bf16 v[108:111], v[182:185], v[156:159], v[108:111]
	ds_read_b128 v[182:185], v207 offset:42640
	v_exp_f32_e32 v74, v74
	s_waitcnt lgkmcnt(2)
	v_mfma_f32_16x16x32_bf16 v[112:115], v[186:189], v[132:135], v[112:115]
	v_exp_f32_e32 v75, v75
	v_mfma_f32_16x16x32_bf16 v[116:119], v[186:189], v[156:159], v[116:119]
	ds_read_b128 v[186:189], v207 offset:53392
	v_add_f32_e32 v224, v224, v74
	v_add_f32_e32 v224, v224, v75
	v_mfma_f32_16x16x32_bf16 v[120:123], v[190:193], v[132:135], v[120:123]
	v_cvt_pk_bf16_f32 v67, v74, v75
	v_mfma_f32_16x16x32_bf16 v[124:127], v[190:193], v[156:159], v[124:127]
	ds_read_b128 v[190:193], v207 offset:54928
	v_exp_f32_e32 v68, v68
	s_waitcnt lgkmcnt(2)
	v_mfma_f32_16x16x32_bf16 v[96:99], v[178:181], v[136:139], v[96:99]
	v_exp_f32_e32 v69, v69
	v_mfma_f32_16x16x32_bf16 v[100:103], v[178:181], v[160:163], v[100:103]
	ds_read_b128 v[178:181], v208 offset:41168
	v_add_f32_e32 v225, v68, v69
	v_cvt_pk_bf16_f32 v68, v68, v69
	v_mfma_f32_16x16x32_bf16 v[104:107], v[182:185], v[136:139], v[104:107]
	v_exp_f32_e32 v70, v70
	v_mfma_f32_16x16x32_bf16 v[108:111], v[182:185], v[160:163], v[108:111]
	ds_read_b128 v[182:185], v208 offset:42704
	v_exp_f32_e32 v71, v71
	s_waitcnt lgkmcnt(2)
	v_mfma_f32_16x16x32_bf16 v[112:115], v[186:189], v[136:139], v[112:115]
	v_add_f32_e32 v225, v225, v70
	v_add_f32_e32 v225, v225, v71
	v_mfma_f32_16x16x32_bf16 v[116:119], v[186:189], v[160:163], v[116:119]
	ds_read_b128 v[186:189], v208 offset:53456
	v_cvt_pk_bf16_f32 v69, v70, v71
	s_cmp_ge_i32 s22, s17
	s_cbranch_scc1 .La3_nd4
	s_add_i32 m0, s58, 0x2000
	s_nop 0
	global_load_lds_dwordx4 v203, s[62:63]
.La3_nd4:
	v_mfma_f32_16x16x32_bf16 v[120:123], v[190:193], v[136:139], v[120:123]
	v_exp_f32_e32 v76, v76
	v_mfma_f32_16x16x32_bf16 v[124:127], v[190:193], v[160:163], v[124:127]
	ds_read_b128 v[190:193], v208 offset:54992
	v_exp_f32_e32 v77, v77
	s_waitcnt lgkmcnt(2)
	v_mfma_f32_16x16x32_bf16 v[96:99], v[178:181], v[140:143], v[96:99]
	v_add_f32_e32 v225, v225, v76
	v_add_f32_e32 v225, v225, v77
	v_mfma_f32_16x16x32_bf16 v[100:103], v[178:181], v[164:167], v[100:103]
	ds_read_b128 v[178:181], v207 offset:41232
	v_cvt_pk_bf16_f32 v70, v76, v77
	v_mfma_f32_16x16x32_bf16 v[104:107], v[182:185], v[140:143], v[104:107]
	v_exp_f32_e32 v78, v78
	v_mfma_f32_16x16x32_bf16 v[108:111], v[182:185], v[164:167], v[108:111]
	ds_read_b128 v[182:185], v207 offset:42768
	v_exp_f32_e32 v79, v79
	s_waitcnt lgkmcnt(2)
	v_mfma_f32_16x16x32_bf16 v[112:115], v[186:189], v[140:143], v[112:115]
	v_add_f32_e32 v225, v225, v78
	v_add_f32_e32 v225, v225, v79
	v_mfma_f32_16x16x32_bf16 v[116:119], v[186:189], v[164:167], v[116:119]
	ds_read_b128 v[186:189], v207 offset:53520
	v_cvt_pk_bf16_f32 v71, v78, v79
	v_mfma_f32_16x16x32_bf16 v[120:123], v[190:193], v[140:143], v[120:123]
	v_exp_f32_e32 v80, v80
	v_mfma_f32_16x16x32_bf16 v[124:127], v[190:193], v[164:167], v[124:127]
	ds_read_b128 v[190:193], v207 offset:55056
	v_exp_f32_e32 v81, v81
	s_waitcnt lgkmcnt(2)
	v_mfma_f32_16x16x32_bf16 v[96:99], v[178:181], v[144:147], v[96:99]
	v_add_f32_e32 v224, v224, v80
	v_add_f32_e32 v224, v224, v81
	v_mfma_f32_16x16x32_bf16 v[100:103], v[178:181], v[168:171], v[100:103]
	ds_read_b128 v[178:181], v208 offset:41296
	v_cvt_pk_bf16_f32 v80, v80, v81
	v_mfma_f32_16x16x32_bf16 v[104:107], v[182:185], v[144:147], v[104:107]
	v_exp_f32_e32 v82, v82
	v_mfma_f32_16x16x32_bf16 v[108:111], v[182:185], v[168:171], v[108:111]
	ds_read_b128 v[182:185], v208 offset:42832
	v_exp_f32_e32 v83, v83
	s_waitcnt lgkmcnt(2)
	v_mfma_f32_16x16x32_bf16 v[112:115], v[186:189], v[144:147], v[112:115]
	v_add_f32_e32 v224, v224, v82
	v_add_f32_e32 v224, v224, v83
	v_mfma_f32_16x16x32_bf16 v[116:119], v[186:189], v[168:171], v[116:119]
	ds_read_b128 v[186:189], v208 offset:53584
	v_cvt_pk_bf16_f32 v81, v82, v83
	s_cmp_ge_i32 s22, s17
	s_cbranch_scc1 .La3_nd5
	s_add_i32 m0, s58, 0x4000
	s_nop 0
	global_load_lds_dwordx4 v204, s[62:63]
; __device__ __forceinline__ unsigned cvt_pk_bf16(float lo, float hi) { unsigned r; asm volatile("v_cvt_pk_bf16_f32 %0, %1, %2" : "=v"(r) : "v"(lo), "v"(hi)); return r; }
; __device__ __forceinline__ float fast_exp2(float x) { return __builtin_amdgcn_exp2f(x); }
; #define LGK(n, f) asm volatile("s_waitcnt lgkmcnt(%1)" : "+v"(f) : "n"(n))
; #define ATT_VRD(j) DSR(fr_[(j) & 3], vad[(j) >> 2], ((j) & 3) * 4096)
; __device__ __forceinline__ void attn_phase(int wv, const bf16_t* Q, const bf16_t* Kf, const bf16_t* Vt, const bf16_t* proj, bf16_t* mixed, LAS unsigned char* lds) { LIDS
;     ...
;                     if (64 * t + 63 > qw0) {
; #pragma unroll
;                         for (int kb = 0; kb < 2; ++kb)
; #pragma unroll
;                             for (int j = 0; j < 16; ++j) { const int key = 64 * t + 32 * kb + 16 * (j >> 3) + 8 * h + (j & 7); if (key > q) s[kb][j] = -1e30f; }
;                     }
;     ...
;                     float ps = 0.f;
; #pragma unroll
;                     for (int kb = 0; kb < 2; ++kb)
; #pragma unroll
;                         for (int j = 0; j < 16; ++j) { s[kb][j] = fast_exp2(s[kb][j] - mrun); ps += s[kb][j]; }
;                     lsum += ps;
; #pragma unroll
;                     for (int c = 0; c < 4; ++c) {
;                         const int kb = c >> 1, sx = c & 1;
;                         u32x4 pw;
; #pragma unroll
;                         for (int j = 0; j < 4; ++j) pw[j] = cvt_pk_bf16(s[kb][8 * sx + 2 * j], s[kb][8 * sx + 2 * j + 1]);
;                         const bf16x8 pf = __builtin_bit_cast(bf16x8, pw);
; #pragma unroll
;                         for (int bb = 0; bb < 4; ++bb) {
;                             const int j = c * 4 + bb;
;                             LGK(j < 13 ? 3 : 15 - j, fr_[j & 3]);
;                             o[bb] = __builtin_amdgcn_mfma_f32_32x32x16_bf16(fr_[j & 3], pf, o[bb], 0, 0, 0);
;                             if (j + 4 < 16) ATT_VRD(j + 4);
;                         }
.La3_nd5:
	v_mfma_f32_16x16x32_bf16 v[120:123], v[190:193], v[144:147], v[120:123]
	v_exp_f32_e32 v88, v88
	v_mfma_f32_16x16x32_bf16 v[124:127], v[190:193], v[168:171], v[124:127]
	ds_read_b128 v[190:193], v208 offset:55120
	v_exp_f32_e32 v89, v89
	s_waitcnt lgkmcnt(2)
	v_mfma_f32_16x16x32_bf16 v[96:99], v[178:181], v[148:151], v[96:99]
	v_add_f32_e32 v224, v224, v88
	v_add_f32_e32 v224, v224, v89
	v_mfma_f32_16x16x32_bf16 v[100:103], v[178:181], v[172:175], v[100:103]
	ds_read_b128 v[178:181], v209 offset:24592
	v_cvt_pk_bf16_f32 v82, v88, v89
	v_mfma_f32_16x16x32_bf16 v[104:107], v[182:185], v[148:151], v[104:107]
	v_exp_f32_e32 v90, v90
	v_mfma_f32_16x16x32_bf16 v[108:111], v[182:185], v[172:175], v[108:111]
	ds_read_b128 v[182:185], v209 offset:26640
	v_exp_f32_e32 v91, v91
	s_waitcnt lgkmcnt(2)
	v_mfma_f32_16x16x32_bf16 v[112:115], v[186:189], v[148:151], v[112:115]
	v_add_f32_e32 v224, v224, v90
	v_add_f32_e32 v224, v224, v91
	v_mfma_f32_16x16x32_bf16 v[116:119], v[186:189], v[172:175], v[116:119]
	ds_read_b128 v[186:189], v209 offset:28688
	v_cvt_pk_bf16_f32 v83, v90, v91
	v_mfma_f32_16x16x32_bf16 v[120:123], v[190:193], v[148:151], v[120:123]
	v_exp_f32_e32 v84, v84
	v_mfma_f32_16x16x32_bf16 v[124:127], v[190:193], v[172:175], v[124:127]
	ds_read_b128 v[190:193], v209 offset:30736
	v_exp_f32_e32 v85, v85
	s_waitcnt lgkmcnt(2)
	v_mfma_f32_16x16x32_bf16 v[0:3], v[178:181], v[64:67], v[0:3]
	v_add_f32_e32 v225, v225, v84
	v_add_f32_e32 v225, v225, v85
	v_mfma_f32_16x16x32_bf16 v[4:7], v[178:181], v[68:71], v[4:7]
	ds_read_b128 v[178:181], v209 offset:32784
	v_cvt_pk_bf16_f32 v84, v84, v85
	v_mfma_f32_16x16x32_bf16 v[8:11], v[182:185], v[64:67], v[8:11]
	v_exp_f32_e32 v86, v86
	v_mfma_f32_16x16x32_bf16 v[12:15], v[182:185], v[68:71], v[12:15]
	ds_read_b128 v[182:185], v209 offset:34832
	v_exp_f32_e32 v87, v87
	s_waitcnt lgkmcnt(2)
	v_mfma_f32_16x16x32_bf16 v[16:19], v[186:189], v[64:67], v[16:19]
	v_add_f32_e32 v225, v225, v86
	v_add_f32_e32 v225, v225, v87
	v_mfma_f32_16x16x32_bf16 v[20:23], v[186:189], v[68:71], v[20:23]
	ds_read_b128 v[186:189], v209 offset:36880
	v_cvt_pk_bf16_f32 v85, v86, v87
	s_cmp_ge_i32 s24, s17
	s_cbranch_scc1 .La3_nd6
	s_add_i32 m0, s58, 0x10000
	s_nop 0
	global_load_lds_dwordx4 v205, s[72:73]
.La3_nd6:
	v_mfma_f32_16x16x32_bf16 v[24:27], v[190:193], v[64:67], v[24:27]
	v_exp_f32_e32 v92, v92
	v_mfma_f32_16x16x32_bf16 v[28:31], v[190:193], v[68:71], v[28:31]
	ds_read_b128 v[190:193], v209 offset:38928
	v_exp_f32_e32 v93, v93
	s_waitcnt lgkmcnt(2)
	v_mfma_f32_16x16x32_bf16 v[32:35], v[178:181], v[64:67], v[32:35]
	v_add_f32_e32 v225, v225, v92
	v_add_f32_e32 v225, v225, v93
	v_mfma_f32_16x16x32_bf16 v[36:39], v[178:181], v[68:71], v[36:39]
	ds_read_b128 v[178:181], v210 offset:24592
	v_cvt_pk_bf16_f32 v86, v92, v93
	v_mfma_f32_16x16x32_bf16 v[40:43], v[182:185], v[64:67], v[40:43]
	v_exp_f32_e32 v94, v94
	v_mfma_f32_16x16x32_bf16 v[44:47], v[182:185], v[68:71], v[44:47]
	ds_read_b128 v[182:185], v210 offset:26640
	s_cmp_lg_u32 s24, s18
	s_cbranch_scc1 .La3_nomask2
	s_lshl_b32 s23, s18, 6
	v_subrev_u32_e32 v221, s23, v231
	v_cmp_le_i32_e32 vcc, 0, v221
	s_nop 1
	v_cndmask_b32_e32 v96, v215, v96, vcc
	v_cmp_le_i32_e32 vcc, 1, v221
	s_nop 1
	v_cndmask_b32_e32 v97, v215, v97, vcc
	v_cmp_le_i32_e32 vcc, 2, v221
	s_nop 1
	v_cndmask_b32_e32 v98, v215, v98, vcc
	v_cmp_le_i32_e32 vcc, 3, v221
	s_nop 1
	v_cndmask_b32_e32 v99, v215, v99, vcc
	v_cmp_le_i32_e32 vcc, -16, v221
	s_nop 1
	v_cndmask_b32_e32 v100, v215, v100, vcc
	v_cmp_le_i32_e32 vcc, -15, v221
	s_nop 1
	v_cndmask_b32_e32 v101, v215, v101, vcc
	v_cmp_le_i32_e32 vcc, -14, v221
	s_nop 1
	v_cndmask_b32_e32 v102, v215, v102, vcc
	v_cmp_le_i32_e32 vcc, -13, v221
	s_nop 1
	v_cndmask_b32_e32 v103, v215, v103, vcc
	v_cmp_le_i32_e32 vcc, 4, v221
	s_nop 1
	v_cndmask_b32_e32 v104, v215, v104, vcc
	v_cmp_le_i32_e32 vcc, 5, v221
	s_nop 1
	v_cndmask_b32_e32 v105, v215, v105, vcc
	v_cmp_le_i32_e32 vcc, 6, v221
	s_nop 1
	v_cndmask_b32_e32 v106, v215, v106, vcc
	v_cmp_le_i32_e32 vcc, 7, v221
	s_nop 1
	v_cndmask_b32_e32 v107, v215, v107, vcc
	v_cmp_le_i32_e32 vcc, -12, v221
	s_nop 1
	v_cndmask_b32_e32 v108, v215, v108, vcc
	v_cmp_le_i32_e32 vcc, -11, v221
	s_nop 1
	v_cndmask_b32_e32 v109, v215, v109, vcc
	v_cmp_le_i32_e32 vcc, -10, v221
	s_nop 1
	v_cndmask_b32_e32 v110, v215, v110, vcc
	v_cmp_le_i32_e32 vcc, -9, v221
	s_nop 1
	v_cndmask_b32_e32 v111, v215, v111, vcc
	v_cmp_le_i32_e32 vcc, 32, v221
	s_nop 1
	v_cndmask_b32_e32 v112, v215, v112, vcc
	v_cmp_le_i32_e32 vcc, 33, v221
	s_nop 1
	v_cndmask_b32_e32 v113, v215, v113, vcc
	v_cmp_le_i32_e32 vcc, 34, v221
	s_nop 1
	v_cndmask_b32_e32 v114, v215, v114, vcc
	v_cmp_le_i32_e32 vcc, 35, v221
	s_nop 1
	v_cndmask_b32_e32 v115, v215, v115, vcc
	v_cmp_le_i32_e32 vcc, 16, v221
	s_nop 1
	v_cndmask_b32_e32 v116, v215, v116, vcc
	v_cmp_le_i32_e32 vcc, 17, v221
	s_nop 1
	v_cndmask_b32_e32 v117, v215, v117, vcc
	v_cmp_le_i32_e32 vcc, 18, v221
	s_nop 1
	v_cndmask_b32_e32 v118, v215, v118, vcc
	v_cmp_le_i32_e32 vcc, 19, v221
	s_nop 1
	v_cndmask_b32_e32 v119, v215, v119, vcc
	v_cmp_le_i32_e32 vcc, 36, v221
	s_nop 1
	v_cndmask_b32_e32 v120, v215, v120, vcc
	v_cmp_le_i32_e32 vcc, 37, v221
	s_nop 1
	v_cndmask_b32_e32 v121, v215, v121, vcc
	v_cmp_le_i32_e32 vcc, 38, v221
	s_nop 1
	v_cndmask_b32_e32 v122, v215, v122, vcc
	v_cmp_le_i32_e32 vcc, 39, v221
	s_nop 1
	v_cndmask_b32_e32 v123, v215, v123, vcc
	v_cmp_le_i32_e32 vcc, 20, v221
	s_nop 1
	v_cndmask_b32_e32 v124, v215, v124, vcc
	v_cmp_le_i32_e32 vcc, 21, v221
	s_nop 1
	v_cndmask_b32_e32 v125, v215, v125, vcc
	v_cmp_le_i32_e32 vcc, 22, v221
	s_nop 1
	v_cndmask_b32_e32 v126, v215, v126, vcc
	v_cmp_le_i32_e32 vcc, 23, v221
	s_nop 1
	v_cndmask_b32_e32 v127, v215, v127, vcc
; __device__ __forceinline__ unsigned cvt_pk_bf16(float lo, float hi) { unsigned r; asm volatile("v_cvt_pk_bf16_f32 %0, %1, %2" : "=v"(r) : "v"(lo), "v"(hi)); return r; }
; __device__ __forceinline__ float fast_exp2(float x) { return __builtin_amdgcn_exp2f(x); }
; #define LGK(n, f) asm volatile("s_waitcnt lgkmcnt(%1)" : "+v"(f) : "n"(n))
; #define ATT_VRD(j) DSR(fr_[(j) & 3], vad[(j) >> 2], ((j) & 3) * 4096)
; __device__ __forceinline__ void attn_phase(int wv, const bf16_t* Q, const bf16_t* Kf, const bf16_t* Vt, const bf16_t* proj, bf16_t* mixed, LAS unsigned char* lds) { LIDS
;     ...
;                     float mx = -1e30f;
; #pragma unroll
;                     for (int kb = 0; kb < 2; ++kb)
; #pragma unroll
;                         for (int j = 0; j < 16; ++j) mx = fmaxf(mx, s[kb][j]);
;                     mx = fmaxf(mx, __shfl_xor(mx, 32));
;                     if (__builtin_amdgcn_ballot_w64(mx > mrun + 8.0f) != 0ull) {
;                         const float mnew = fmaxf(mrun, mx), alpha = fast_exp2(mrun - mnew); mrun = mnew;
;                         lsum *= alpha;
; #pragma unroll
;                         for (int bb = 0; bb < 4; ++bb)
; #pragma unroll
;                             for (int j = 0; j < 16; ++j) o[bb][j] *= alpha;
;                     }
;                     float ps = 0.f;
; #pragma unroll
;                     for (int kb = 0; kb < 2; ++kb)
; #pragma unroll
;                         for (int j = 0; j < 16; ++j) { s[kb][j] = fast_exp2(s[kb][j] - mrun); ps += s[kb][j]; }
;                     lsum += ps;
; #pragma unroll
;                     for (int c = 0; c < 4; ++c) {
;                         const int kb = c >> 1, sx = c & 1;
;                         u32x4 pw;
; #pragma unroll
;                         for (int j = 0; j < 4; ++j) pw[j] = cvt_pk_bf16(s[kb][8 * sx + 2 * j], s[kb][8 * sx + 2 * j + 1]);
;                         const bf16x8 pf = __builtin_bit_cast(bf16x8, pw);
; #pragma unroll
;                         for (int bb = 0; bb < 4; ++bb) {
;                             const int j = c * 4 + bb;
;                             LGK(j < 13 ? 3 : 15 - j, fr_[j & 3]);
;                             o[bb] = __builtin_amdgcn_mfma_f32_32x32x16_bf16(fr_[j & 3], pf, o[bb], 0, 0, 0);
;                             if (j + 4 < 16) ATT_VRD(j + 4);
;                         }
.La3_nomask2:
	v_exp_f32_e32 v95, v95
	s_waitcnt lgkmcnt(2)
	v_mfma_f32_16x16x32_bf16 v[48:51], v[186:189], v[64:67], v[48:51]
	v_add_f32_e32 v225, v225, v94
	v_add_f32_e32 v225, v225, v95
	v_mfma_f32_16x16x32_bf16 v[52:55], v[186:189], v[68:71], v[52:55]
	ds_read_b128 v[186:189], v210 offset:28688
	v_cvt_pk_bf16_f32 v87, v94, v95
	v_add_f32_e32 v226, v226, v224
	v_mfma_f32_16x16x32_bf16 v[56:59], v[190:193], v[64:67], v[56:59]
	v_add_f32_e32 v227, v227, v225
	v_max3_f32 v218, v96, v97, v98
	v_mfma_f32_16x16x32_bf16 v[60:63], v[190:193], v[68:71], v[60:63]
	ds_read_b128 v[190:193], v210 offset:30736
	v_max3_f32 v218, v218, v99, v104
	v_max3_f32 v218, v218, v105, v106
	s_waitcnt lgkmcnt(2)
	v_mfma_f32_16x16x32_bf16 v[0:3], v[178:181], v[80:83], v[0:3]
	v_max3_f32 v218, v218, v107, v112
	v_max3_f32 v218, v218, v113, v114
	v_mfma_f32_16x16x32_bf16 v[4:7], v[178:181], v[84:87], v[4:7]
	ds_read_b128 v[178:181], v210 offset:32784
	v_max3_f32 v218, v218, v115, v120
	v_max3_f32 v218, v218, v121, v122
	v_mfma_f32_16x16x32_bf16 v[8:11], v[182:185], v[80:83], v[8:11]
	v_max_f32_e32 v218, v218, v123
	v_max3_f32 v219, v100, v101, v102
	v_mfma_f32_16x16x32_bf16 v[12:15], v[182:185], v[84:87], v[12:15]
	ds_read_b128 v[182:185], v210 offset:34832
	v_max3_f32 v219, v219, v103, v108
	v_max3_f32 v219, v219, v109, v110
	s_waitcnt lgkmcnt(2)
	v_mfma_f32_16x16x32_bf16 v[16:19], v[186:189], v[80:83], v[16:19]
	v_max3_f32 v219, v219, v111, v116
	v_max3_f32 v219, v219, v117, v118
	v_mfma_f32_16x16x32_bf16 v[20:23], v[186:189], v[84:87], v[20:23]
	ds_read_b128 v[186:189], v210 offset:36880
	v_max3_f32 v219, v219, v119, v124
	v_max3_f32 v219, v219, v125, v126
	s_cmp_ge_i32 s24, s17
	s_cbranch_scc1 .La3_nd7
	s_add_i32 m0, s58, 0x12000
	s_nop 0
	global_load_lds_dwordx4 v206, s[72:73]
.La3_nd7:
	v_mfma_f32_16x16x32_bf16 v[24:27], v[190:193], v[80:83], v[24:27]
	v_max_f32_e32 v219, v219, v127
	s_nop 1
	v_permlane16_swap_b32_e32 v218, v219
	v_mfma_f32_16x16x32_bf16 v[28:31], v[190:193], v[84:87], v[28:31]
	ds_read_b128 v[190:193], v210 offset:38928
	v_max_f32_e32 v218, v218, v219
	v_mov_b32_e32 v219, v218
	s_waitcnt lgkmcnt(2)
	v_mfma_f32_16x16x32_bf16 v[32:35], v[178:181], v[80:83], v[32:35]
	v_permlane32_swap_b32_e32 v218, v219
	v_max_f32_e32 v218, v218, v219
	v_mfma_f32_16x16x32_bf16 v[36:39], v[178:181], v[84:87], v[36:39]
	v_mov_b32_e32 v219, v218
	s_nop 1
	v_permlane16_swap_b32_e32 v218, v219
	v_mfma_f32_16x16x32_bf16 v[40:43], v[182:185], v[80:83], v[40:43]
	v_max_f32_e32 v220, v218, v219
	v_mfma_f32_16x16x32_bf16 v[44:47], v[182:185], v[84:87], v[44:47]
	s_waitcnt lgkmcnt(0)
	v_mfma_f32_16x16x32_bf16 v[48:51], v[186:189], v[80:83], v[48:51]
	v_mfma_f32_16x16x32_bf16 v[52:55], v[186:189], v[84:87], v[52:55]
	v_mfma_f32_16x16x32_bf16 v[56:59], v[190:193], v[80:83], v[56:59]
	v_mfma_f32_16x16x32_bf16 v[60:63], v[190:193], v[84:87], v[60:63]
	v_cmp_gt_f32_e32 vcc, v220, v230
	s_cbranch_vccnz .La3_rare0

; #define LAS __attribute__((address_space(3)))
; __device__ __forceinline__ unsigned cvt_pk_bf16(float lo, float hi) { unsigned r; asm volatile("v_cvt_pk_bf16_f32 %0, %1, %2" : "=v"(r) : "v"(lo), "v"(hi)); return r; }
; __device__ __forceinline__ float fast_exp2(float x) { return __builtin_amdgcn_exp2f(x); }
; #define LGK(n, f) asm volatile("s_waitcnt lgkmcnt(%1)" : "+v"(f) : "n"(n))
; __device__ __forceinline__ void attn_phase(int wv, const bf16_t* Q, const bf16_t* Kf, const bf16_t* Vt, const bf16_t* proj, bf16_t* mixed, LAS unsigned char* lds) { LIDS
;     ...
;                 asm volatile("s_waitcnt vmcnt(0)" ::: "memory"); __builtin_amdgcn_s_barrier(); asm volatile("" ::: "memory");
;                 if (t + 1 < nt) ATT_ISSUE(t + 1, b ^ 1);
;                 if (64 * t <= qw0 + 31) {
;                     LAS unsigned char* kb_ = lds + b * ATT_STAGE; LAS unsigned char* vb_ = kb_ + ATT_KB;
;                     f32x16 s[2];
; #pragma unroll
;                     for (int kb = 0; kb < 2; ++kb)
; #pragma unroll
;                         for (int j = 0; j < 16; ++j) s[kb][j] = zf;
;                     unsigned kad[4];
; #pragma unroll
;                     for (int kl = 0; kl < 4; ++kl) kad[kl] = (unsigned)(size_t)kb_ + (unsigned)koffl[kl];
;                     bf16x8 fr_[4];
;     ...
;                     ATT_KRD(0); ATT_KRD(1); ATT_KRD(2); ATT_KRD(3);
; #pragma unroll
;                     for (int i = 0; i < 24; ++i) {
;                         LGK(i < 21 ? 3 : 23 - i, fr_[i & 3]);
;                         s[i & 1] = __builtin_amdgcn_mfma_f32_32x32x16_bf16(fr_[i & 3], qf[i >> 1], s[i & 1], 0, 0, 0);
;                         if (i + 4 < 24) ATT_KRD(i + 4);
;                     }
;     ...
;                     float ps = 0.f;
; #pragma unroll
;                     for (int kb = 0; kb < 2; ++kb)
; #pragma unroll
;                         for (int j = 0; j < 16; ++j) { s[kb][j] = fast_exp2(s[kb][j] - mrun); ps += s[kb][j]; }
;                     lsum += ps;
; #pragma unroll
;                     for (int c = 0; c < 4; ++c) {
;                         const int kb = c >> 1, sx = c & 1;
;                         u32x4 pw;
; #pragma unroll
;                         for (int j = 0; j < 4; ++j) pw[j] = cvt_pk_bf16(s[kb][8 * sx + 2 * j], s[kb][8 * sx + 2 * j + 1]);
;                         const bf16x8 pf = __builtin_bit_cast(bf16x8, pw);
.La3_top1:
	s_waitcnt vmcnt(0)
	s_barrier
	s_add_i32 s22, s19, 2
	s_add_i32 s24, s19, 1
	s_cmp_gt_i32 s19, s18
	s_cbranch_scc1 .La3_idle1
	s_cmp_eq_u32 s19, s18
	s_cbranch_scc1 .La3_drain1
	ds_read_b128 v[178:181], v207 offset:16
	ds_read_b128 v[182:185], v207 offset:1552
	ds_read_b128 v[186:189], v207 offset:12304
	ds_read_b128 v[190:193], v207 offset:13840
	s_waitcnt lgkmcnt(2)
	v_mfma_f32_16x16x32_bf16 v[64:67], v[178:181], v[128:131], v[194:197]
	v_exp_f32_e32 v96, v96
	v_mfma_f32_16x16x32_bf16 v[68:71], v[178:181], v[152:155], v[198:201]
	ds_read_b128 v[178:181], v208 offset:80
	v_exp_f32_e32 v97, v97
	v_mfma_f32_16x16x32_bf16 v[72:75], v[182:185], v[128:131], v[194:197]
	v_add_f32_e32 v224, v96, v97
	v_cvt_pk_bf16_f32 v96, v96, v97
	v_mfma_f32_16x16x32_bf16 v[76:79], v[182:185], v[152:155], v[198:201]
	ds_read_b128 v[182:185], v208 offset:1616
	v_exp_f32_e32 v98, v98
	s_waitcnt lgkmcnt(2)
	v_mfma_f32_16x16x32_bf16 v[80:83], v[186:189], v[128:131], v[194:197]
	v_exp_f32_e32 v99, v99
	v_mfma_f32_16x16x32_bf16 v[84:87], v[186:189], v[152:155], v[198:201]
	ds_read_b128 v[186:189], v208 offset:12368
	v_add_f32_e32 v224, v224, v98
	v_add_f32_e32 v224, v224, v99
	s_cmp_ge_i32 s22, s17
	s_cbranch_scc1 .La3_nd9
	s_add_i32 m0, s58, 0xa000
	s_nop 0
	global_load_lds_dwordx4 v202, s[62:63]
.La3_nd9:
	v_mfma_f32_16x16x32_bf16 v[88:91], v[190:193], v[128:131], v[194:197]
	v_cvt_pk_bf16_f32 v97, v98, v99
	v_mfma_f32_16x16x32_bf16 v[92:95], v[190:193], v[152:155], v[198:201]
	ds_read_b128 v[190:193], v208 offset:13904
	v_exp_f32_e32 v104, v104
	s_waitcnt lgkmcnt(2)
	v_mfma_f32_16x16x32_bf16 v[64:67], v[178:181], v[132:135], v[64:67]
	v_exp_f32_e32 v105, v105
	v_mfma_f32_16x16x32_bf16 v[68:71], v[178:181], v[156:159], v[68:71]
	ds_read_b128 v[178:181], v207 offset:144
	v_add_f32_e32 v224, v224, v104
	v_add_f32_e32 v224, v224, v105
	v_mfma_f32_16x16x32_bf16 v[72:75], v[182:185], v[132:135], v[72:75]
	v_cvt_pk_bf16_f32 v98, v104, v105
	v_mfma_f32_16x16x32_bf16 v[76:79], v[182:185], v[156:159], v[76:79]
	ds_read_b128 v[182:185], v207 offset:1680
	v_exp_f32_e32 v106, v106
	s_waitcnt lgkmcnt(2)
	v_mfma_f32_16x16x32_bf16 v[80:83], v[186:189], v[132:135], v[80:83]
	v_exp_f32_e32 v107, v107
	v_mfma_f32_16x16x32_bf16 v[84:87], v[186:189], v[156:159], v[84:87]
	ds_read_b128 v[186:189], v207 offset:12432
	v_add_f32_e32 v224, v224, v106
	v_add_f32_e32 v224, v224, v107
	v_mfma_f32_16x16x32_bf16 v[88:91], v[190:193], v[132:135], v[88:91]
	v_cvt_pk_bf16_f32 v99, v106, v107
	v_mfma_f32_16x16x32_bf16 v[92:95], v[190:193], v[156:159], v[92:95]
	ds_read_b128 v[190:193], v207 offset:13968
	v_exp_f32_e32 v100, v100
	s_waitcnt lgkmcnt(2)
	v_mfma_f32_16x16x32_bf16 v[64:67], v[178:181], v[136:139], v[64:67]
	v_exp_f32_e32 v101, v101
	v_mfma_f32_16x16x32_bf16 v[68:71], v[178:181], v[160:163], v[68:71]
	ds_read_b128 v[178:181], v208 offset:208
	v_add_f32_e32 v225, v100, v101
	v_cvt_pk_bf16_f32 v100, v100, v101
	v_mfma_f32_16x16x32_bf16 v[72:75], v[182:185], v[136:139], v[72:75]
	v_exp_f32_e32 v102, v102
	v_mfma_f32_16x16x32_bf16 v[76:79], v[182:185], v[160:163], v[76:79]
	ds_read_b128 v[182:185], v208 offset:1744
	v_exp_f32_e32 v103, v103
	s_waitcnt lgkmcnt(2)
	v_mfma_f32_16x16x32_bf16 v[80:83], v[186:189], v[136:139], v[80:83]
	v_add_f32_e32 v225, v225, v102
	v_add_f32_e32 v225, v225, v103
	v_mfma_f32_16x16x32_bf16 v[84:87], v[186:189], v[160:163], v[84:87]
	ds_read_b128 v[186:189], v208 offset:12496
	v_cvt_pk_bf16_f32 v101, v102, v103
	s_cmp_ge_i32 s22, s17
	s_cbranch_scc1 .La3_nd10
	s_add_i32 m0, s58, 0xc000
	s_nop 0
	global_load_lds_dwordx4 v203, s[62:63]
.La3_nd10:
	v_mfma_f32_16x16x32_bf16 v[88:91], v[190:193], v[136:139], v[88:91]
	v_exp_f32_e32 v108, v108
	v_mfma_f32_16x16x32_bf16 v[92:95], v[190:193], v[160:163], v[92:95]
	ds_read_b128 v[190:193], v208 offset:14032
	v_exp_f32_e32 v109, v109
	s_waitcnt lgkmcnt(2)
	v_mfma_f32_16x16x32_bf16 v[64:67], v[178:181], v[140:143], v[64:67]
	v_add_f32_e32 v225, v225, v108
	v_add_f32_e32 v225, v225, v109
	v_mfma_f32_16x16x32_bf16 v[68:71], v[178:181], v[164:167], v[68:71]
	ds_read_b128 v[178:181], v207 offset:272
	v_cvt_pk_bf16_f32 v102, v108, v109
	v_mfma_f32_16x16x32_bf16 v[72:75], v[182:185], v[140:143], v[72:75]
	v_exp_f32_e32 v110, v110
	v_mfma_f32_16x16x32_bf16 v[76:79], v[182:185], v[164:167], v[76:79]
	ds_read_b128 v[182:185], v207 offset:1808
	v_exp_f32_e32 v111, v111
	s_waitcnt lgkmcnt(2)
	v_mfma_f32_16x16x32_bf16 v[80:83], v[186:189], v[140:143], v[80:83]
	v_add_f32_e32 v225, v225, v110
	v_add_f32_e32 v225, v225, v111
	v_mfma_f32_16x16x32_bf16 v[84:87], v[186:189], v[164:167], v[84:87]
	ds_read_b128 v[186:189], v207 offset:12560
	v_cvt_pk_bf16_f32 v103, v110, v111
	v_mfma_f32_16x16x32_bf16 v[88:91], v[190:193], v[140:143], v[88:91]
	v_exp_f32_e32 v112, v112
	v_mfma_f32_16x16x32_bf16 v[92:95], v[190:193], v[164:167], v[92:95]
	ds_read_b128 v[190:193], v207 offset:14096
	v_exp_f32_e32 v113, v113
	s_waitcnt lgkmcnt(2)
	v_mfma_f32_16x16x32_bf16 v[64:67], v[178:181], v[144:147], v[64:67]
	v_add_f32_e32 v224, v224, v112
	v_add_f32_e32 v224, v224, v113
	v_mfma_f32_16x16x32_bf16 v[68:71], v[178:181], v[168:171], v[68:71]
	ds_read_b128 v[178:181], v208 offset:336
	v_cvt_pk_bf16_f32 v112, v112, v113
	v_mfma_f32_16x16x32_bf16 v[72:75], v[182:185], v[144:147], v[72:75]
	v_exp_f32_e32 v114, v114
	v_mfma_f32_16x16x32_bf16 v[76:79], v[182:185], v[168:171], v[76:79]
	ds_read_b128 v[182:185], v208 offset:1872
	v_exp_f32_e32 v115, v115
	s_waitcnt lgkmcnt(2)
	v_mfma_f32_16x16x32_bf16 v[80:83], v[186:189], v[144:147], v[80:83]
	v_add_f32_e32 v224, v224, v114
	v_add_f32_e32 v224, v224, v115
	v_mfma_f32_16x16x32_bf16 v[84:87], v[186:189], v[168:171], v[84:87]
	ds_read_b128 v[186:189], v208 offset:12624
	v_cvt_pk_bf16_f32 v113, v114, v115
	s_cmp_ge_i32 s22, s17
	s_cbranch_scc1 .La3_nd11
	s_add_i32 m0, s58, 0xe000
	s_nop 0
	global_load_lds_dwordx4 v204, s[62:63]
; #define LGK(n, f) asm volatile("s_waitcnt lgkmcnt(%1)" : "+v"(f) : "n"(n))
; #define ATT_KRD(i) DSR(fr_[(i) & 3], kad[((i) >> 1) & 3], ((i) & 1) * (32 * 384) + ((i) >> 3) * 128)
; #define ATT_VRD(j) DSR(fr_[(j) & 3], vad[(j) >> 2], ((j) & 3) * 4096)
; __device__ __forceinline__ void attn_phase(int wv, const bf16_t* Q, const bf16_t* Kf, const bf16_t* Vt, const bf16_t* proj, bf16_t* mixed, LAS unsigned char* lds) { LIDS
;     ...
;                     ATT_KRD(0); ATT_KRD(1); ATT_KRD(2); ATT_KRD(3);
; #pragma unroll
;                     for (int i = 0; i < 24; ++i) {
;                         LGK(i < 21 ? 3 : 23 - i, fr_[i & 3]);
;                         s[i & 1] = __builtin_amdgcn_mfma_f32_32x32x16_bf16(fr_[i & 3], qf[i >> 1], s[i & 1], 0, 0, 0);
;                         if (i + 4 < 24) ATT_KRD(i + 4);
;                     }
;     ...
;                     unsigned vad[4];
; #pragma unroll
;                     for (int c = 0; c < 4; ++c) vad[c] = (unsigned)(size_t)vb_ + (unsigned)voffl[c];
;     ...
;                     ATT_VRD(0); ATT_VRD(1); ATT_VRD(2); ATT_VRD(3);
;                     if (64 * t + 63 > qw0) {
; #pragma unroll
;                         for (int kb = 0; kb < 2; ++kb)
; #pragma unroll
;                             for (int j = 0; j < 16; ++j) { const int key = 64 * t + 32 * kb + 16 * (j >> 3) + 8 * h + (j & 7); if (key > q) s[kb][j] = -1e30f; }
;                     }
;     ...
;                         for (int bb = 0; bb < 4; ++bb) {
;                             const int j = c * 4 + bb;
;                             LGK(j < 13 ? 3 : 15 - j, fr_[j & 3]);
;                             o[bb] = __builtin_amdgcn_mfma_f32_32x32x16_bf16(fr_[j & 3], pf, o[bb], 0, 0, 0);
;                             if (j + 4 < 16) ATT_VRD(j + 4);
.La3_nd11:
	v_mfma_f32_16x16x32_bf16 v[88:91], v[190:193], v[144:147], v[88:91]
	v_exp_f32_e32 v120, v120
	v_mfma_f32_16x16x32_bf16 v[92:95], v[190:193], v[168:171], v[92:95]
	ds_read_b128 v[190:193], v208 offset:14160
	v_exp_f32_e32 v121, v121
	s_waitcnt lgkmcnt(2)
	v_mfma_f32_16x16x32_bf16 v[64:67], v[178:181], v[148:151], v[64:67]
	v_add_f32_e32 v224, v224, v120
	v_add_f32_e32 v224, v224, v121
	v_mfma_f32_16x16x32_bf16 v[68:71], v[178:181], v[172:175], v[68:71]
	ds_read_b128 v[178:181], v211 offset:32784
	v_cvt_pk_bf16_f32 v114, v120, v121
	v_mfma_f32_16x16x32_bf16 v[72:75], v[182:185], v[148:151], v[72:75]
	v_exp_f32_e32 v122, v122
	v_mfma_f32_16x16x32_bf16 v[76:79], v[182:185], v[172:175], v[76:79]
	ds_read_b128 v[182:185], v211 offset:34832
	v_exp_f32_e32 v123, v123
	s_waitcnt lgkmcnt(2)
	v_mfma_f32_16x16x32_bf16 v[80:83], v[186:189], v[148:151], v[80:83]
	v_add_f32_e32 v224, v224, v122
	v_add_f32_e32 v224, v224, v123
	v_mfma_f32_16x16x32_bf16 v[84:87], v[186:189], v[172:175], v[84:87]
	ds_read_b128 v[186:189], v211 offset:36880
	v_cvt_pk_bf16_f32 v115, v122, v123
	v_mfma_f32_16x16x32_bf16 v[88:91], v[190:193], v[148:151], v[88:91]
	v_exp_f32_e32 v116, v116
	v_mfma_f32_16x16x32_bf16 v[92:95], v[190:193], v[172:175], v[92:95]
	ds_read_b128 v[190:193], v211 offset:38928
	v_exp_f32_e32 v117, v117
	s_waitcnt lgkmcnt(2)
	v_mfma_f32_16x16x32_bf16 v[0:3], v[178:181], v[96:99], v[0:3]
	v_add_f32_e32 v225, v225, v116
	v_add_f32_e32 v225, v225, v117
	v_mfma_f32_16x16x32_bf16 v[4:7], v[178:181], v[100:103], v[4:7]
	ds_read_b128 v[178:181], v211 offset:40976
	v_cvt_pk_bf16_f32 v116, v116, v117
	v_mfma_f32_16x16x32_bf16 v[8:11], v[182:185], v[96:99], v[8:11]
	v_exp_f32_e32 v118, v118
	v_mfma_f32_16x16x32_bf16 v[12:15], v[182:185], v[100:103], v[12:15]
	ds_read_b128 v[182:185], v211 offset:43024
	v_exp_f32_e32 v119, v119
	s_waitcnt lgkmcnt(2)
	v_mfma_f32_16x16x32_bf16 v[16:19], v[186:189], v[96:99], v[16:19]
	v_add_f32_e32 v225, v225, v118
	v_add_f32_e32 v225, v225, v119
	v_mfma_f32_16x16x32_bf16 v[20:23], v[186:189], v[100:103], v[20:23]
	ds_read_b128 v[186:189], v211 offset:45072
	v_cvt_pk_bf16_f32 v117, v118, v119
	s_cmp_ge_i32 s24, s17
	s_cbranch_scc1 .La3_nd12
	s_add_i32 m0, s58, 0x6000
	s_nop 0
	global_load_lds_dwordx4 v205, s[72:73]
.La3_nd12:
	v_mfma_f32_16x16x32_bf16 v[24:27], v[190:193], v[96:99], v[24:27]
	v_exp_f32_e32 v124, v124
	v_mfma_f32_16x16x32_bf16 v[28:31], v[190:193], v[100:103], v[28:31]
	ds_read_b128 v[190:193], v211 offset:47120
	v_exp_f32_e32 v125, v125
	s_waitcnt lgkmcnt(2)
	v_mfma_f32_16x16x32_bf16 v[32:35], v[178:181], v[96:99], v[32:35]
	v_add_f32_e32 v225, v225, v124
	v_add_f32_e32 v225, v225, v125
	v_mfma_f32_16x16x32_bf16 v[36:39], v[178:181], v[100:103], v[36:39]
	ds_read_b128 v[178:181], v212 offset:32784
	v_cvt_pk_bf16_f32 v118, v124, v125
	v_mfma_f32_16x16x32_bf16 v[40:43], v[182:185], v[96:99], v[40:43]
	v_exp_f32_e32 v126, v126
	v_mfma_f32_16x16x32_bf16 v[44:47], v[182:185], v[100:103], v[44:47]
	ds_read_b128 v[182:185], v212 offset:34832
	s_cmp_lg_u32 s24, s18
	s_cbranch_scc1 .La3_nomask8
	s_lshl_b32 s23, s18, 6
	v_subrev_u32_e32 v221, s23, v231
	v_cmp_le_i32_e32 vcc, 0, v221
	s_nop 1
	v_cndmask_b32_e32 v64, v215, v64, vcc
	v_cmp_le_i32_e32 vcc, 1, v221
	s_nop 1
	v_cndmask_b32_e32 v65, v215, v65, vcc
	v_cmp_le_i32_e32 vcc, 2, v221
	s_nop 1
	v_cndmask_b32_e32 v66, v215, v66, vcc
	v_cmp_le_i32_e32 vcc, 3, v221
	s_nop 1
	v_cndmask_b32_e32 v67, v215, v67, vcc
	v_cmp_le_i32_e32 vcc, -16, v221
	s_nop 1
	v_cndmask_b32_e32 v68, v215, v68, vcc
	v_cmp_le_i32_e32 vcc, -15, v221
	s_nop 1
	v_cndmask_b32_e32 v69, v215, v69, vcc
	v_cmp_le_i32_e32 vcc, -14, v221
	s_nop 1
	v_cndmask_b32_e32 v70, v215, v70, vcc
	v_cmp_le_i32_e32 vcc, -13, v221
	s_nop 1
	v_cndmask_b32_e32 v71, v215, v71, vcc
	v_cmp_le_i32_e32 vcc, 4, v221
	s_nop 1
	v_cndmask_b32_e32 v72, v215, v72, vcc
	v_cmp_le_i32_e32 vcc, 5, v221
	s_nop 1
	v_cndmask_b32_e32 v73, v215, v73, vcc
	v_cmp_le_i32_e32 vcc, 6, v221
	s_nop 1
	v_cndmask_b32_e32 v74, v215, v74, vcc
	v_cmp_le_i32_e32 vcc, 7, v221
	s_nop 1
	v_cndmask_b32_e32 v75, v215, v75, vcc
	v_cmp_le_i32_e32 vcc, -12, v221
	s_nop 1
	v_cndmask_b32_e32 v76, v215, v76, vcc
	v_cmp_le_i32_e32 vcc, -11, v221
	s_nop 1
	v_cndmask_b32_e32 v77, v215, v77, vcc
	v_cmp_le_i32_e32 vcc, -10, v221
	s_nop 1
	v_cndmask_b32_e32 v78, v215, v78, vcc
	v_cmp_le_i32_e32 vcc, -9, v221
	s_nop 1
	v_cndmask_b32_e32 v79, v215, v79, vcc
	v_cmp_le_i32_e32 vcc, 32, v221
	s_nop 1
	v_cndmask_b32_e32 v80, v215, v80, vcc
	v_cmp_le_i32_e32 vcc, 33, v221
	s_nop 1
	v_cndmask_b32_e32 v81, v215, v81, vcc
	v_cmp_le_i32_e32 vcc, 34, v221
	s_nop 1
	v_cndmask_b32_e32 v82, v215, v82, vcc
	v_cmp_le_i32_e32 vcc, 35, v221
	s_nop 1
	v_cndmask_b32_e32 v83, v215, v83, vcc
	v_cmp_le_i32_e32 vcc, 16, v221
	s_nop 1
	v_cndmask_b32_e32 v84, v215, v84, vcc
	v_cmp_le_i32_e32 vcc, 17, v221
	s_nop 1
	v_cndmask_b32_e32 v85, v215, v85, vcc
	v_cmp_le_i32_e32 vcc, 18, v221
	s_nop 1
	v_cndmask_b32_e32 v86, v215, v86, vcc
	v_cmp_le_i32_e32 vcc, 19, v221
	s_nop 1
	v_cndmask_b32_e32 v87, v215, v87, vcc
	v_cmp_le_i32_e32 vcc, 36, v221
	s_nop 1
	v_cndmask_b32_e32 v88, v215, v88, vcc
	v_cmp_le_i32_e32 vcc, 37, v221
	s_nop 1
	v_cndmask_b32_e32 v89, v215, v89, vcc
	v_cmp_le_i32_e32 vcc, 38, v221
	s_nop 1
	v_cndmask_b32_e32 v90, v215, v90, vcc
	v_cmp_le_i32_e32 vcc, 39, v221
	s_nop 1
	v_cndmask_b32_e32 v91, v215, v91, vcc
	v_cmp_le_i32_e32 vcc, 20, v221
	s_nop 1
	v_cndmask_b32_e32 v92, v215, v92, vcc
	v_cmp_le_i32_e32 vcc, 21, v221
	s_nop 1
	v_cndmask_b32_e32 v93, v215, v93, vcc
	v_cmp_le_i32_e32 vcc, 22, v221
	s_nop 1
	v_cndmask_b32_e32 v94, v215, v94, vcc
	v_cmp_le_i32_e32 vcc, 23, v221
	s_nop 1
	v_cndmask_b32_e32 v95, v215, v95, vcc
; #define LGK(n, f) asm volatile("s_waitcnt lgkmcnt(%1)" : "+v"(f) : "n"(n))
; #define ATT_VRD(j) DSR(fr_[(j) & 3], vad[(j) >> 2], ((j) & 3) * 4096)
; __device__ __forceinline__ void attn_phase(int wv, const bf16_t* Q, const bf16_t* Kf, const bf16_t* Vt, const bf16_t* proj, bf16_t* mixed, LAS unsigned char* lds) { LIDS
;     ...
;                     float mx = -1e30f;
; #pragma unroll
;                     for (int kb = 0; kb < 2; ++kb)
; #pragma unroll
;                         for (int j = 0; j < 16; ++j) mx = fmaxf(mx, s[kb][j]);
;                     mx = fmaxf(mx, __shfl_xor(mx, 32));
;                     if (__builtin_amdgcn_ballot_w64(mx > mrun + 8.0f) != 0ull) {
;     ...
;                         for (int bb = 0; bb < 4; ++bb) {
;                             const int j = c * 4 + bb;
;                             LGK(j < 13 ? 3 : 15 - j, fr_[j & 3]);
;                             o[bb] = __builtin_amdgcn_mfma_f32_32x32x16_bf16(fr_[j & 3], pf, o[bb], 0, 0, 0);
;                             if (j + 4 < 16) ATT_VRD(j + 4);
;                         }
.La3_nomask8:
	v_exp_f32_e32 v127, v127
	s_waitcnt lgkmcnt(2)
	v_mfma_f32_16x16x32_bf16 v[48:51], v[186:189], v[96:99], v[48:51]
	v_add_f32_e32 v225, v225, v126
	v_add_f32_e32 v225, v225, v127
	v_mfma_f32_16x16x32_bf16 v[52:55], v[186:189], v[100:103], v[52:55]
	ds_read_b128 v[186:189], v212 offset:36880
	v_cvt_pk_bf16_f32 v119, v126, v127
	v_add_f32_e32 v226, v226, v224
	v_mfma_f32_16x16x32_bf16 v[56:59], v[190:193], v[96:99], v[56:59]
	v_add_f32_e32 v227, v227, v225
	v_max3_f32 v218, v64, v65, v66
	v_mfma_f32_16x16x32_bf16 v[60:63], v[190:193], v[100:103], v[60:63]
	ds_read_b128 v[190:193], v212 offset:38928
	v_max3_f32 v218, v218, v67, v72
	v_max3_f32 v218, v218, v73, v74
	s_waitcnt lgkmcnt(2)
	v_mfma_f32_16x16x32_bf16 v[0:3], v[178:181], v[112:115], v[0:3]
	v_max3_f32 v218, v218, v75, v80
	v_max3_f32 v218, v218, v81, v82
	v_mfma_f32_16x16x32_bf16 v[4:7], v[178:181], v[116:119], v[4:7]
	ds_read_b128 v[178:181], v212 offset:40976
	v_max3_f32 v218, v218, v83, v88
	v_max3_f32 v218, v218, v89, v90
	v_mfma_f32_16x16x32_bf16 v[8:11], v[182:185], v[112:115], v[8:11]
	v_max_f32_e32 v218, v218, v91
	v_max3_f32 v219, v68, v69, v70
	v_mfma_f32_16x16x32_bf16 v[12:15], v[182:185], v[116:119], v[12:15]
	ds_read_b128 v[182:185], v212 offset:43024
	v_max3_f32 v219, v219, v71, v76
	v_max3_f32 v219, v219, v77, v78
	s_waitcnt lgkmcnt(2)
	v_mfma_f32_16x16x32_bf16 v[16:19], v[186:189], v[112:115], v[16:19]
	v_max3_f32 v219, v219, v79, v84
	v_max3_f32 v219, v219, v85, v86
	v_mfma_f32_16x16x32_bf16 v[20:23], v[186:189], v[116:119], v[20:23]
	ds_read_b128 v[186:189], v212 offset:45072
	v_max3_f32 v219, v219, v87, v92
	v_max3_f32 v219, v219, v93, v94
	s_cmp_ge_i32 s24, s17
	s_cbranch_scc1 .La3_nd13
	s_add_i32 m0, s58, 0x8000
	s_nop 0
	global_load_lds_dwordx4 v206, s[72:73]
.La3_nd13:
	v_mfma_f32_16x16x32_bf16 v[24:27], v[190:193], v[112:115], v[24:27]
	v_max_f32_e32 v219, v219, v95
	s_nop 1
	v_permlane16_swap_b32_e32 v218, v219
	v_mfma_f32_16x16x32_bf16 v[28:31], v[190:193], v[116:119], v[28:31]
	ds_read_b128 v[190:193], v212 offset:47120
	v_max_f32_e32 v218, v218, v219
	v_mov_b32_e32 v219, v218
	s_waitcnt lgkmcnt(2)
	v_mfma_f32_16x16x32_bf16 v[32:35], v[178:181], v[112:115], v[32:35]
	v_permlane32_swap_b32_e32 v218, v219
	v_max_f32_e32 v218, v218, v219
	v_mfma_f32_16x16x32_bf16 v[36:39], v[178:181], v[116:119], v[36:39]
	v_mov_b32_e32 v219, v218
	s_nop 1
	v_permlane16_swap_b32_e32 v218, v219
	v_mfma_f32_16x16x32_bf16 v[40:43], v[182:185], v[112:115], v[40:43]
	v_max_f32_e32 v220, v218, v219
	v_mfma_f32_16x16x32_bf16 v[44:47], v[182:185], v[116:119], v[44:47]
	s_waitcnt lgkmcnt(0)
	v_mfma_f32_16x16x32_bf16 v[48:51], v[186:189], v[112:115], v[48:51]
	v_mfma_f32_16x16x32_bf16 v[52:55], v[186:189], v[116:119], v[52:55]
	v_mfma_f32_16x16x32_bf16 v[56:59], v[190:193], v[112:115], v[56:59]
	v_mfma_f32_16x16x32_bf16 v[60:63], v[190:193], v[116:119], v[60:63]
	v_cmp_gt_f32_e32 vcc, v220, v230
	s_cbranch_vccnz .La3_rare1

; __device__ __forceinline__ unsigned cvt_pk_bf16(float lo, float hi) { unsigned r; asm volatile("v_cvt_pk_bf16_f32 %0, %1, %2" : "=v"(r) : "v"(lo), "v"(hi)); return r; }
; __device__ __forceinline__ float bflo(unsigned w) { return __uint_as_float(w << 16); }
; __device__ __forceinline__ float bfhi(unsigned w) { return __uint_as_float(w & 0xffff0000u); }
; __device__ __forceinline__ float siluf_(float x) { return x * sigmoidf_(x); }
; __device__ __forceinline__ int lane_id_asm() { int x; asm volatile("v_mbcnt_lo_u32_b32 %0, -1, 0\n\tv_mbcnt_hi_u32_b32 %0, -1, %0" : "=&v"(x)); return x; }
; __device__ __forceinline__ void attn_phase(int wv, const bf16_t* Q, const bf16_t* Kf, const bf16_t* Vt, const bf16_t* proj, bf16_t* mixed, LAS unsigned char* lds) { LIDS
;     ...
;             const float ltot = lsum + __shfl_xor(lsum, 32), inv = 1.0f / ltot;
;             const int l2 = lane_id_asm(), h2 = l2 >> 5, q2 = qb * 256 + 32 * wid + (l2 & 31);
;             u32x2 gwv[16];
; #pragma unroll
;             for (int e = 0; e < 16; ++e) gwv[e] = *(const u32x2*)(proj + (size_t)q2 * NIN + C_GM + head * 128 + 32 * (e >> 2) + 8 * (e & 3) + 4 * h2);
;             __builtin_amdgcn_sched_barrier(0);
; #pragma unroll
;             for (int bb = 0; bb < 4; ++bb)
; #pragma unroll
;                 for (int jp = 0; jp < 2; ++jp) {
;                     u32x2 wv2[2];
; #pragma unroll
;                     for (int e = 0; e < 2; ++e) { const int gq = 2 * jp + e; const u32x2 gw = gwv[bb * 4 + gq];
;                         wv2[e][0] = cvt_pk_bf16(o[bb][4 * gq] * inv * siluf_(bflo(gw[0])), o[bb][4 * gq + 1] * inv * siluf_(bfhi(gw[0])));
;                         wv2[e][1] = cvt_pk_bf16(o[bb][4 * gq + 2] * inv * siluf_(bflo(gw[1])), o[bb][4 * gq + 3] * inv * siluf_(bfhi(gw[1]))); }
;                     const auto r0 = __builtin_amdgcn_permlane32_swap(wv2[0][0], wv2[1][0], false, false);
;                     const auto r1 = __builtin_amdgcn_permlane32_swap(wv2[0][1], wv2[1][1], false, false);
;                     u32x4 ov; ov[0] = r0[0]; ov[1] = r1[0]; ov[2] = r0[1]; ov[3] = r1[1];
;                     *(u32x4*)(mixed + (size_t)q2 * DM + head * 128 + 32 * bb + 16 * jp + 8 * h2) = ov;
;                     __builtin_amdgcn_sched_barrier(0);
;                 }
.La3_exit:
	s_nop 9
	v_permlane16_swap_b32_e32 v226, v227
	v_add_f32_e32 v226, v226, v227
	v_mov_b32_e32 v227, v226
	s_nop 1
	v_permlane32_swap_b32_e32 v226, v227
	v_add_f32_e32 v226, v226, v227
	v_mov_b32_e32 v227, v226
	s_nop 1
	v_permlane16_swap_b32_e32 v226, v227
	v_div_scale_f32 v220, s[26:27], v226, v226, 1.0
	v_rcp_f32_e32 v221, v220
	s_nop 0
	v_fma_f32 v222, -v220, v221, 1.0
	v_fmac_f32_e32 v221, v222, v221
	v_div_scale_f32 v222, vcc, 1.0, v226, 1.0
	v_mul_f32_e32 v223, v222, v221
	v_fma_f32 v236, -v220, v223, v222
	v_fmac_f32_e32 v223, v236, v221
	v_fma_f32 v220, -v220, v223, v222
	v_div_fmas_f32 v220, v220, v221, v223
	v_div_fixup_f32 v226, v220, v226, 1.0
	v_div_scale_f32 v220, s[26:27], v227, v227, 1.0
	v_rcp_f32_e32 v221, v220
	s_nop 0
	v_fma_f32 v222, -v220, v221, 1.0
	v_fmac_f32_e32 v221, v222, v221
	v_div_scale_f32 v222, vcc, 1.0, v227, 1.0
	v_mul_f32_e32 v223, v222, v221
	v_fma_f32 v236, -v220, v223, v222
	v_fmac_f32_e32 v223, v236, v221
	v_fma_f32 v220, -v220, v223, v222
	v_div_fmas_f32 v220, v220, v221, v223
	v_div_fixup_f32 v227, v220, v227, 1.0
	global_load_dwordx2 v[64:65], v244, s[12:13] offset:0
	global_load_dwordx2 v[66:67], v245, s[12:13] offset:0
	global_load_dwordx2 v[68:69], v244, s[12:13] offset:32
	global_load_dwordx2 v[70:71], v245, s[12:13] offset:32
	global_load_dwordx2 v[72:73], v244, s[12:13] offset:64
	global_load_dwordx2 v[74:75], v245, s[12:13] offset:64
	global_load_dwordx2 v[76:77], v244, s[12:13] offset:96
	global_load_dwordx2 v[78:79], v245, s[12:13] offset:96
	global_load_dwordx2 v[80:81], v244, s[12:13] offset:128
	global_load_dwordx2 v[82:83], v245, s[12:13] offset:128
	global_load_dwordx2 v[84:85], v244, s[12:13] offset:160
	global_load_dwordx2 v[86:87], v245, s[12:13] offset:160
	global_load_dwordx2 v[88:89], v244, s[12:13] offset:192
	global_load_dwordx2 v[90:91], v245, s[12:13] offset:192
	global_load_dwordx2 v[92:93], v244, s[12:13] offset:224
	global_load_dwordx2 v[94:95], v245, s[12:13] offset:224
	s_waitcnt vmcnt(0)
	v_lshlrev_b32_e32 v236, 16, v64
	v_mul_f32_e32 v237, 0xbfb8aa3b, v236
	v_exp_f32_e32 v237, v237
	s_nop 0
	v_add_f32_e32 v237, 1.0, v237
	v_rcp_f32_e32 v237, v237
	v_mul_f32_e32 v238, v0, v226
	v_mul_f32_e32 v237, v237, v236
	v_mul_f32_e32 v240, v238, v237
	v_and_b32_e32 v236, 0xffff0000, v64
	v_mul_f32_e32 v237, 0xbfb8aa3b, v236
	v_exp_f32_e32 v237, v237
	s_nop 0
	v_add_f32_e32 v237, 1.0, v237
	v_rcp_f32_e32 v237, v237
	v_mul_f32_e32 v238, v1, v226
	v_mul_f32_e32 v237, v237, v236
	v_mul_f32_e32 v241, v238, v237
	v_lshlrev_b32_e32 v236, 16, v65
	v_mul_f32_e32 v237, 0xbfb8aa3b, v236
	v_exp_f32_e32 v237, v237
	s_nop 0
	v_add_f32_e32 v237, 1.0, v237
	v_rcp_f32_e32 v237, v237
	v_mul_f32_e32 v238, v2, v226
	v_mul_f32_e32 v237, v237, v236
	v_mul_f32_e32 v242, v238, v237
	v_and_b32_e32 v236, 0xffff0000, v65
	v_mul_f32_e32 v237, 0xbfb8aa3b, v236
	v_exp_f32_e32 v237, v237
	s_nop 0
	v_add_f32_e32 v237, 1.0, v237
	v_rcp_f32_e32 v237, v237
	v_mul_f32_e32 v238, v3, v226
	v_mul_f32_e32 v237, v237, v236
	v_mul_f32_e32 v243, v238, v237
	v_cvt_pk_bf16_f32 v238, v240, v241
	v_cvt_pk_bf16_f32 v239, v242, v243
	global_store_dwordx2 v246, v[238:239], s[20:21] offset:0
	s_nop 1
	v_lshlrev_b32_e32 v236, 16, v66
	v_mul_f32_e32 v237, 0xbfb8aa3b, v236
	v_exp_f32_e32 v237, v237
	s_nop 0
	v_add_f32_e32 v237, 1.0, v237
	v_rcp_f32_e32 v237, v237
	v_mul_f32_e32 v238, v4, v227
	v_mul_f32_e32 v237, v237, v236
	v_mul_f32_e32 v240, v238, v237
	v_and_b32_e32 v236, 0xffff0000, v66
	v_mul_f32_e32 v237, 0xbfb8aa3b, v236
	v_exp_f32_e32 v237, v237
	s_nop 0
	v_add_f32_e32 v237, 1.0, v237
	v_rcp_f32_e32 v237, v237
	v_mul_f32_e32 v238, v5, v227
	v_mul_f32_e32 v237, v237, v236
	v_mul_f32_e32 v241, v238, v237
	v_lshlrev_b32_e32 v236, 16, v67
	v_mul_f32_e32 v237, 0xbfb8aa3b, v236
	v_exp_f32_e32 v237, v237
	s_nop 0
	v_add_f32_e32 v237, 1.0, v237
	v_rcp_f32_e32 v237, v237
	v_mul_f32_e32 v238, v6, v227
	v_mul_f32_e32 v237, v237, v236
	v_mul_f32_e32 v242, v238, v237
	v_and_b32_e32 v236, 0xffff0000, v67
	v_mul_f32_e32 v237, 0xbfb8aa3b, v236
	v_exp_f32_e32 v237, v237
	s_nop 0
	v_add_f32_e32 v237, 1.0, v237
	v_rcp_f32_e32 v237, v237
	v_mul_f32_e32 v238, v7, v227
	v_mul_f32_e32 v237, v237, v236
	v_mul_f32_e32 v243, v238, v237
	v_cvt_pk_bf16_f32 v238, v240, v241
	v_cvt_pk_bf16_f32 v239, v242, v243
	global_store_dwordx2 v247, v[238:239], s[20:21] offset:0
	s_nop 1
	v_lshlrev_b32_e32 v236, 16, v68
	v_mul_f32_e32 v237, 0xbfb8aa3b, v236
	v_exp_f32_e32 v237, v237
	s_nop 0
	v_add_f32_e32 v237, 1.0, v237
	v_rcp_f32_e32 v237, v237
	v_mul_f32_e32 v238, v8, v226
	v_mul_f32_e32 v237, v237, v236
	v_mul_f32_e32 v240, v238, v237
	v_and_b32_e32 v236, 0xffff0000, v68
	v_mul_f32_e32 v237, 0xbfb8aa3b, v236
	v_exp_f32_e32 v237, v237
	s_nop 0
	v_add_f32_e32 v237, 1.0, v237
	v_rcp_f32_e32 v237, v237
	v_mul_f32_e32 v238, v9, v226
	v_mul_f32_e32 v237, v237, v236
	v_mul_f32_e32 v241, v238, v237
	v_lshlrev_b32_e32 v236, 16, v69
	v_mul_f32_e32 v237, 0xbfb8aa3b, v236
	v_exp_f32_e32 v237, v237
	s_nop 0
	v_add_f32_e32 v237, 1.0, v237
	v_rcp_f32_e32 v237, v237
	v_mul_f32_e32 v238, v10, v226
	v_mul_f32_e32 v237, v237, v236
	v_mul_f32_e32 v242, v238, v237
	v_and_b32_e32 v236, 0xffff0000, v69
	v_mul_f32_e32 v237, 0xbfb8aa3b, v236
	v_exp_f32_e32 v237, v237
	s_nop 0
	v_add_f32_e32 v237, 1.0, v237
	v_rcp_f32_e32 v237, v237
	v_mul_f32_e32 v238, v11, v226
	v_mul_f32_e32 v237, v237, v236
	v_mul_f32_e32 v243, v238, v237
	v_cvt_pk_bf16_f32 v238, v240, v241
	v_cvt_pk_bf16_f32 v239, v242, v243
	global_store_dwordx2 v246, v[238:239], s[20:21] offset:32
	s_nop 1
	v_lshlrev_b32_e32 v236, 16, v70
	v_mul_f32_e32 v237, 0xbfb8aa3b, v236
	v_exp_f32_e32 v237, v237
	s_nop 0
; __device__ __forceinline__ unsigned cvt_pk_bf16(float lo, float hi) { unsigned r; asm volatile("v_cvt_pk_bf16_f32 %0, %1, %2" : "=v"(r) : "v"(lo), "v"(hi)); return r; }
; __device__ __forceinline__ float bflo(unsigned w) { return __uint_as_float(w << 16); }
; __device__ __forceinline__ float bfhi(unsigned w) { return __uint_as_float(w & 0xffff0000u); }
; __device__ __forceinline__ float siluf_(float x) { return x * sigmoidf_(x); }
; __device__ __forceinline__ void attn_phase(int wv, const bf16_t* Q, const bf16_t* Kf, const bf16_t* Vt, const bf16_t* proj, bf16_t* mixed, LAS unsigned char* lds) { LIDS
;     ...
;             for (int bb = 0; bb < 4; ++bb)
; #pragma unroll
;                 for (int jp = 0; jp < 2; ++jp) {
;                     u32x2 wv2[2];
; #pragma unroll
;                     for (int e = 0; e < 2; ++e) { const int gq = 2 * jp + e; const u32x2 gw = gwv[bb * 4 + gq];
;                         wv2[e][0] = cvt_pk_bf16(o[bb][4 * gq] * inv * siluf_(bflo(gw[0])), o[bb][4 * gq + 1] * inv * siluf_(bfhi(gw[0])));
;                         wv2[e][1] = cvt_pk_bf16(o[bb][4 * gq + 2] * inv * siluf_(bflo(gw[1])), o[bb][4 * gq + 3] * inv * siluf_(bfhi(gw[1]))); }
;                     const auto r0 = __builtin_amdgcn_permlane32_swap(wv2[0][0], wv2[1][0], false, false);
;                     const auto r1 = __builtin_amdgcn_permlane32_swap(wv2[0][1], wv2[1][1], false, false);
;                     u32x4 ov; ov[0] = r0[0]; ov[1] = r1[0]; ov[2] = r0[1]; ov[3] = r1[1];
;                     *(u32x4*)(mixed + (size_t)q2 * DM + head * 128 + 32 * bb + 16 * jp + 8 * h2) = ov;
;                     __builtin_amdgcn_sched_barrier(0);
;                 }
	v_add_f32_e32 v237, 1.0, v237
	v_rcp_f32_e32 v237, v237
	v_mul_f32_e32 v238, v12, v227
	v_mul_f32_e32 v237, v237, v236
	v_mul_f32_e32 v240, v238, v237
	v_and_b32_e32 v236, 0xffff0000, v70
	v_mul_f32_e32 v237, 0xbfb8aa3b, v236
	v_exp_f32_e32 v237, v237
	s_nop 0
	v_add_f32_e32 v237, 1.0, v237
	v_rcp_f32_e32 v237, v237
	v_mul_f32_e32 v238, v13, v227
	v_mul_f32_e32 v237, v237, v236
	v_mul_f32_e32 v241, v238, v237
	v_lshlrev_b32_e32 v236, 16, v71
	v_mul_f32_e32 v237, 0xbfb8aa3b, v236
	v_exp_f32_e32 v237, v237
	s_nop 0
	v_add_f32_e32 v237, 1.0, v237
	v_rcp_f32_e32 v237, v237
	v_mul_f32_e32 v238, v14, v227
	v_mul_f32_e32 v237, v237, v236
	v_mul_f32_e32 v242, v238, v237
	v_and_b32_e32 v236, 0xffff0000, v71
	v_mul_f32_e32 v237, 0xbfb8aa3b, v236
	v_exp_f32_e32 v237, v237
	s_nop 0
	v_add_f32_e32 v237, 1.0, v237
	v_rcp_f32_e32 v237, v237
	v_mul_f32_e32 v238, v15, v227
	v_mul_f32_e32 v237, v237, v236
	v_mul_f32_e32 v243, v238, v237
	v_cvt_pk_bf16_f32 v238, v240, v241
	v_cvt_pk_bf16_f32 v239, v242, v243
	global_store_dwordx2 v247, v[238:239], s[20:21] offset:32
	s_nop 1
	v_lshlrev_b32_e32 v236, 16, v72
	v_mul_f32_e32 v237, 0xbfb8aa3b, v236
	v_exp_f32_e32 v237, v237
	s_nop 0
	v_add_f32_e32 v237, 1.0, v237
	v_rcp_f32_e32 v237, v237
	v_mul_f32_e32 v238, v16, v226
	v_mul_f32_e32 v237, v237, v236
	v_mul_f32_e32 v240, v238, v237
	v_and_b32_e32 v236, 0xffff0000, v72
	v_mul_f32_e32 v237, 0xbfb8aa3b, v236
	v_exp_f32_e32 v237, v237
	s_nop 0
	v_add_f32_e32 v237, 1.0, v237
	v_rcp_f32_e32 v237, v237
	v_mul_f32_e32 v238, v17, v226
	v_mul_f32_e32 v237, v237, v236
	v_mul_f32_e32 v241, v238, v237
	v_lshlrev_b32_e32 v236, 16, v73
	v_mul_f32_e32 v237, 0xbfb8aa3b, v236
	v_exp_f32_e32 v237, v237
	s_nop 0
	v_add_f32_e32 v237, 1.0, v237
	v_rcp_f32_e32 v237, v237
	v_mul_f32_e32 v238, v18, v226
	v_mul_f32_e32 v237, v237, v236
	v_mul_f32_e32 v242, v238, v237
	v_and_b32_e32 v236, 0xffff0000, v73
	v_mul_f32_e32 v237, 0xbfb8aa3b, v236
	v_exp_f32_e32 v237, v237
	s_nop 0
	v_add_f32_e32 v237, 1.0, v237
	v_rcp_f32_e32 v237, v237
	v_mul_f32_e32 v238, v19, v226
	v_mul_f32_e32 v237, v237, v236
	v_mul_f32_e32 v243, v238, v237
	v_cvt_pk_bf16_f32 v238, v240, v241
	v_cvt_pk_bf16_f32 v239, v242, v243
	global_store_dwordx2 v246, v[238:239], s[20:21] offset:64
	s_nop 1
	v_lshlrev_b32_e32 v236, 16, v74
	v_mul_f32_e32 v237, 0xbfb8aa3b, v236
	v_exp_f32_e32 v237, v237
	s_nop 0
	v_add_f32_e32 v237, 1.0, v237
	v_rcp_f32_e32 v237, v237
	v_mul_f32_e32 v238, v20, v227
	v_mul_f32_e32 v237, v237, v236
	v_mul_f32_e32 v240, v238, v237
	v_and_b32_e32 v236, 0xffff0000, v74
	v_mul_f32_e32 v237, 0xbfb8aa3b, v236
	v_exp_f32_e32 v237, v237
	s_nop 0
	v_add_f32_e32 v237, 1.0, v237
	v_rcp_f32_e32 v237, v237
	v_mul_f32_e32 v238, v21, v227
	v_mul_f32_e32 v237, v237, v236
	v_mul_f32_e32 v241, v238, v237
	v_lshlrev_b32_e32 v236, 16, v75
	v_mul_f32_e32 v237, 0xbfb8aa3b, v236
	v_exp_f32_e32 v237, v237
	s_nop 0
	v_add_f32_e32 v237, 1.0, v237
	v_rcp_f32_e32 v237, v237
	v_mul_f32_e32 v238, v22, v227
	v_mul_f32_e32 v237, v237, v236
	v_mul_f32_e32 v242, v238, v237
	v_and_b32_e32 v236, 0xffff0000, v75
	v_mul_f32_e32 v237, 0xbfb8aa3b, v236
	v_exp_f32_e32 v237, v237
	s_nop 0
	v_add_f32_e32 v237, 1.0, v237
	v_rcp_f32_e32 v237, v237
	v_mul_f32_e32 v238, v23, v227
	v_mul_f32_e32 v237, v237, v236
	v_mul_f32_e32 v243, v238, v237
	v_cvt_pk_bf16_f32 v238, v240, v241
	v_cvt_pk_bf16_f32 v239, v242, v243
	global_store_dwordx2 v247, v[238:239], s[20:21] offset:64
	s_nop 1
	v_lshlrev_b32_e32 v236, 16, v76
	v_mul_f32_e32 v237, 0xbfb8aa3b, v236
	v_exp_f32_e32 v237, v237
	s_nop 0
	v_add_f32_e32 v237, 1.0, v237
	v_rcp_f32_e32 v237, v237
	v_mul_f32_e32 v238, v24, v226
	v_mul_f32_e32 v237, v237, v236
	v_mul_f32_e32 v240, v238, v237
	v_and_b32_e32 v236, 0xffff0000, v76
	v_mul_f32_e32 v237, 0xbfb8aa3b, v236
	v_exp_f32_e32 v237, v237
	s_nop 0
	v_add_f32_e32 v237, 1.0, v237
	v_rcp_f32_e32 v237, v237
	v_mul_f32_e32 v238, v25, v226
	v_mul_f32_e32 v237, v237, v236
	v_mul_f32_e32 v241, v238, v237
	v_lshlrev_b32_e32 v236, 16, v77
	v_mul_f32_e32 v237, 0xbfb8aa3b, v236
	v_exp_f32_e32 v237, v237
	s_nop 0
	v_add_f32_e32 v237, 1.0, v237
	v_rcp_f32_e32 v237, v237
	v_mul_f32_e32 v238, v26, v226
	v_mul_f32_e32 v237, v237, v236
	v_mul_f32_e32 v242, v238, v237
	v_and_b32_e32 v236, 0xffff0000, v77
	v_mul_f32_e32 v237, 0xbfb8aa3b, v236
	v_exp_f32_e32 v237, v237
	s_nop 0
	v_add_f32_e32 v237, 1.0, v237
	v_rcp_f32_e32 v237, v237
	v_mul_f32_e32 v238, v27, v226
	v_mul_f32_e32 v237, v237, v236
	v_mul_f32_e32 v243, v238, v237
	v_cvt_pk_bf16_f32 v238, v240, v241
	v_cvt_pk_bf16_f32 v239, v242, v243
	global_store_dwordx2 v246, v[238:239], s[20:21] offset:96
	s_nop 1
	v_lshlrev_b32_e32 v236, 16, v78
	v_mul_f32_e32 v237, 0xbfb8aa3b, v236
	v_exp_f32_e32 v237, v237
	s_nop 0
	v_add_f32_e32 v237, 1.0, v237
	v_rcp_f32_e32 v237, v237
	v_mul_f32_e32 v238, v28, v227
	v_mul_f32_e32 v237, v237, v236
	v_mul_f32_e32 v240, v238, v237
	v_and_b32_e32 v236, 0xffff0000, v78
	v_mul_f32_e32 v237, 0xbfb8aa3b, v236
	v_exp_f32_e32 v237, v237
	s_nop 0
	v_add_f32_e32 v237, 1.0, v237
	v_rcp_f32_e32 v237, v237
	v_mul_f32_e32 v238, v29, v227
	v_mul_f32_e32 v237, v237, v236
	v_mul_f32_e32 v241, v238, v237
	v_lshlrev_b32_e32 v236, 16, v79
	v_mul_f32_e32 v237, 0xbfb8aa3b, v236
	v_exp_f32_e32 v237, v237
	s_nop 0
	v_add_f32_e32 v237, 1.0, v237
	v_rcp_f32_e32 v237, v237
	v_mul_f32_e32 v238, v30, v227
	v_mul_f32_e32 v237, v237, v236
	v_mul_f32_e32 v242, v238, v237
	v_and_b32_e32 v236, 0xffff0000, v79
	v_mul_f32_e32 v237, 0xbfb8aa3b, v236
	v_exp_f32_e32 v237, v237
	s_nop 0
	v_add_f32_e32 v237, 1.0, v237
	v_rcp_f32_e32 v237, v237
	v_mul_f32_e32 v238, v31, v227
	v_mul_f32_e32 v237, v237, v236
	v_mul_f32_e32 v243, v238, v237
; __device__ __forceinline__ unsigned cvt_pk_bf16(float lo, float hi) { unsigned r; asm volatile("v_cvt_pk_bf16_f32 %0, %1, %2" : "=v"(r) : "v"(lo), "v"(hi)); return r; }
; __device__ __forceinline__ float bflo(unsigned w) { return __uint_as_float(w << 16); }
; __device__ __forceinline__ float bfhi(unsigned w) { return __uint_as_float(w & 0xffff0000u); }
; __device__ __forceinline__ float siluf_(float x) { return x * sigmoidf_(x); }
; __device__ __forceinline__ void attn_phase(int wv, const bf16_t* Q, const bf16_t* Kf, const bf16_t* Vt, const bf16_t* proj, bf16_t* mixed, LAS unsigned char* lds) { LIDS
;     ...
;             for (int bb = 0; bb < 4; ++bb)
; #pragma unroll
;                 for (int jp = 0; jp < 2; ++jp) {
;                     u32x2 wv2[2];
; #pragma unroll
;                     for (int e = 0; e < 2; ++e) { const int gq = 2 * jp + e; const u32x2 gw = gwv[bb * 4 + gq];
;                         wv2[e][0] = cvt_pk_bf16(o[bb][4 * gq] * inv * siluf_(bflo(gw[0])), o[bb][4 * gq + 1] * inv * siluf_(bfhi(gw[0])));
;                         wv2[e][1] = cvt_pk_bf16(o[bb][4 * gq + 2] * inv * siluf_(bflo(gw[1])), o[bb][4 * gq + 3] * inv * siluf_(bfhi(gw[1]))); }
;                     const auto r0 = __builtin_amdgcn_permlane32_swap(wv2[0][0], wv2[1][0], false, false);
;                     const auto r1 = __builtin_amdgcn_permlane32_swap(wv2[0][1], wv2[1][1], false, false);
;                     u32x4 ov; ov[0] = r0[0]; ov[1] = r1[0]; ov[2] = r0[1]; ov[3] = r1[1];
;                     *(u32x4*)(mixed + (size_t)q2 * DM + head * 128 + 32 * bb + 16 * jp + 8 * h2) = ov;
;                     __builtin_amdgcn_sched_barrier(0);
;                 }
	v_cvt_pk_bf16_f32 v238, v240, v241
	v_cvt_pk_bf16_f32 v239, v242, v243
	global_store_dwordx2 v247, v[238:239], s[20:21] offset:96
	s_nop 1
	v_lshlrev_b32_e32 v236, 16, v80
	v_mul_f32_e32 v237, 0xbfb8aa3b, v236
	v_exp_f32_e32 v237, v237
	s_nop 0
	v_add_f32_e32 v237, 1.0, v237
	v_rcp_f32_e32 v237, v237
	v_mul_f32_e32 v238, v32, v226
	v_mul_f32_e32 v237, v237, v236
	v_mul_f32_e32 v240, v238, v237
	v_and_b32_e32 v236, 0xffff0000, v80
	v_mul_f32_e32 v237, 0xbfb8aa3b, v236
	v_exp_f32_e32 v237, v237
	s_nop 0
	v_add_f32_e32 v237, 1.0, v237
	v_rcp_f32_e32 v237, v237
	v_mul_f32_e32 v238, v33, v226
	v_mul_f32_e32 v237, v237, v236
	v_mul_f32_e32 v241, v238, v237
	v_lshlrev_b32_e32 v236, 16, v81
	v_mul_f32_e32 v237, 0xbfb8aa3b, v236
	v_exp_f32_e32 v237, v237
	s_nop 0
	v_add_f32_e32 v237, 1.0, v237
	v_rcp_f32_e32 v237, v237
	v_mul_f32_e32 v238, v34, v226
	v_mul_f32_e32 v237, v237, v236
	v_mul_f32_e32 v242, v238, v237
	v_and_b32_e32 v236, 0xffff0000, v81
	v_mul_f32_e32 v237, 0xbfb8aa3b, v236
	v_exp_f32_e32 v237, v237
	s_nop 0
	v_add_f32_e32 v237, 1.0, v237
	v_rcp_f32_e32 v237, v237
	v_mul_f32_e32 v238, v35, v226
	v_mul_f32_e32 v237, v237, v236
	v_mul_f32_e32 v243, v238, v237
	v_cvt_pk_bf16_f32 v238, v240, v241
	v_cvt_pk_bf16_f32 v239, v242, v243
	global_store_dwordx2 v246, v[238:239], s[20:21] offset:128
	s_nop 1
	v_lshlrev_b32_e32 v236, 16, v82
	v_mul_f32_e32 v237, 0xbfb8aa3b, v236
	v_exp_f32_e32 v237, v237
	s_nop 0
	v_add_f32_e32 v237, 1.0, v237
	v_rcp_f32_e32 v237, v237
	v_mul_f32_e32 v238, v36, v227
	v_mul_f32_e32 v237, v237, v236
	v_mul_f32_e32 v240, v238, v237
	v_and_b32_e32 v236, 0xffff0000, v82
	v_mul_f32_e32 v237, 0xbfb8aa3b, v236
	v_exp_f32_e32 v237, v237
	s_nop 0
	v_add_f32_e32 v237, 1.0, v237
	v_rcp_f32_e32 v237, v237
	v_mul_f32_e32 v238, v37, v227
	v_mul_f32_e32 v237, v237, v236
	v_mul_f32_e32 v241, v238, v237
	v_lshlrev_b32_e32 v236, 16, v83
	v_mul_f32_e32 v237, 0xbfb8aa3b, v236
	v_exp_f32_e32 v237, v237
	s_nop 0
	v_add_f32_e32 v237, 1.0, v237
	v_rcp_f32_e32 v237, v237
	v_mul_f32_e32 v238, v38, v227
	v_mul_f32_e32 v237, v237, v236
	v_mul_f32_e32 v242, v238, v237
	v_and_b32_e32 v236, 0xffff0000, v83
	v_mul_f32_e32 v237, 0xbfb8aa3b, v236
	v_exp_f32_e32 v237, v237
	s_nop 0
	v_add_f32_e32 v237, 1.0, v237
	v_rcp_f32_e32 v237, v237
	v_mul_f32_e32 v238, v39, v227
	v_mul_f32_e32 v237, v237, v236
	v_mul_f32_e32 v243, v238, v237
	v_cvt_pk_bf16_f32 v238, v240, v241
	v_cvt_pk_bf16_f32 v239, v242, v243
	global_store_dwordx2 v247, v[238:239], s[20:21] offset:128
	s_nop 1
	v_lshlrev_b32_e32 v236, 16, v84
	v_mul_f32_e32 v237, 0xbfb8aa3b, v236
	v_exp_f32_e32 v237, v237
	s_nop 0
	v_add_f32_e32 v237, 1.0, v237
	v_rcp_f32_e32 v237, v237
	v_mul_f32_e32 v238, v40, v226
	v_mul_f32_e32 v237, v237, v236
	v_mul_f32_e32 v240, v238, v237
	v_and_b32_e32 v236, 0xffff0000, v84
	v_mul_f32_e32 v237, 0xbfb8aa3b, v236
	v_exp_f32_e32 v237, v237
	s_nop 0
	v_add_f32_e32 v237, 1.0, v237
	v_rcp_f32_e32 v237, v237
	v_mul_f32_e32 v238, v41, v226
	v_mul_f32_e32 v237, v237, v236
	v_mul_f32_e32 v241, v238, v237
	v_lshlrev_b32_e32 v236, 16, v85
	v_mul_f32_e32 v237, 0xbfb8aa3b, v236
	v_exp_f32_e32 v237, v237
	s_nop 0
	v_add_f32_e32 v237, 1.0, v237
	v_rcp_f32_e32 v237, v237
	v_mul_f32_e32 v238, v42, v226
	v_mul_f32_e32 v237, v237, v236
	v_mul_f32_e32 v242, v238, v237
	v_and_b32_e32 v236, 0xffff0000, v85
	v_mul_f32_e32 v237, 0xbfb8aa3b, v236
	v_exp_f32_e32 v237, v237
	s_nop 0
	v_add_f32_e32 v237, 1.0, v237
	v_rcp_f32_e32 v237, v237
	v_mul_f32_e32 v238, v43, v226
	v_mul_f32_e32 v237, v237, v236
	v_mul_f32_e32 v243, v238, v237
	v_cvt_pk_bf16_f32 v238, v240, v241
	v_cvt_pk_bf16_f32 v239, v242, v243
	global_store_dwordx2 v246, v[238:239], s[20:21] offset:160
	s_nop 1
	v_lshlrev_b32_e32 v236, 16, v86
	v_mul_f32_e32 v237, 0xbfb8aa3b, v236
	v_exp_f32_e32 v237, v237
	s_nop 0
	v_add_f32_e32 v237, 1.0, v237
	v_rcp_f32_e32 v237, v237
	v_mul_f32_e32 v238, v44, v227
	v_mul_f32_e32 v237, v237, v236
	v_mul_f32_e32 v240, v238, v237
	v_and_b32_e32 v236, 0xffff0000, v86
	v_mul_f32_e32 v237, 0xbfb8aa3b, v236
	v_exp_f32_e32 v237, v237
	s_nop 0
	v_add_f32_e32 v237, 1.0, v237
	v_rcp_f32_e32 v237, v237
	v_mul_f32_e32 v238, v45, v227
	v_mul_f32_e32 v237, v237, v236
	v_mul_f32_e32 v241, v238, v237
	v_lshlrev_b32_e32 v236, 16, v87
	v_mul_f32_e32 v237, 0xbfb8aa3b, v236
	v_exp_f32_e32 v237, v237
	s_nop 0
	v_add_f32_e32 v237, 1.0, v237
	v_rcp_f32_e32 v237, v237
	v_mul_f32_e32 v238, v46, v227
	v_mul_f32_e32 v237, v237, v236
	v_mul_f32_e32 v242, v238, v237
	v_and_b32_e32 v236, 0xffff0000, v87
	v_mul_f32_e32 v237, 0xbfb8aa3b, v236
	v_exp_f32_e32 v237, v237
	s_nop 0
	v_add_f32_e32 v237, 1.0, v237
	v_rcp_f32_e32 v237, v237
	v_mul_f32_e32 v238, v47, v227
	v_mul_f32_e32 v237, v237, v236
	v_mul_f32_e32 v243, v238, v237
	v_cvt_pk_bf16_f32 v238, v240, v241
	v_cvt_pk_bf16_f32 v239, v242, v243
	global_store_dwordx2 v247, v[238:239], s[20:21] offset:160
	s_nop 1
	v_lshlrev_b32_e32 v236, 16, v88
	v_mul_f32_e32 v237, 0xbfb8aa3b, v236
	v_exp_f32_e32 v237, v237
	s_nop 0
	v_add_f32_e32 v237, 1.0, v237
	v_rcp_f32_e32 v237, v237
	v_mul_f32_e32 v238, v48, v226
	v_mul_f32_e32 v237, v237, v236
	v_mul_f32_e32 v240, v238, v237
	v_and_b32_e32 v236, 0xffff0000, v88
	v_mul_f32_e32 v237, 0xbfb8aa3b, v236
	v_exp_f32_e32 v237, v237
; __device__ __forceinline__ unsigned cvt_pk_bf16(float lo, float hi) { unsigned r; asm volatile("v_cvt_pk_bf16_f32 %0, %1, %2" : "=v"(r) : "v"(lo), "v"(hi)); return r; }
; __device__ __forceinline__ float bflo(unsigned w) { return __uint_as_float(w << 16); }
; __device__ __forceinline__ float bfhi(unsigned w) { return __uint_as_float(w & 0xffff0000u); }
; __device__ __forceinline__ float siluf_(float x) { return x * sigmoidf_(x); }
; __device__ __forceinline__ void attn_phase(int wv, const bf16_t* Q, const bf16_t* Kf, const bf16_t* Vt, const bf16_t* proj, bf16_t* mixed, LAS unsigned char* lds) { LIDS
;     ...
;                 if (t + 1 < nt) ATT_ISSUE(t + 1, b ^ 1);
;     ...
;             for (int bb = 0; bb < 4; ++bb)
; #pragma unroll
;                 for (int jp = 0; jp < 2; ++jp) {
;                     u32x2 wv2[2];
; #pragma unroll
;                     for (int e = 0; e < 2; ++e) { const int gq = 2 * jp + e; const u32x2 gw = gwv[bb * 4 + gq];
;                         wv2[e][0] = cvt_pk_bf16(o[bb][4 * gq] * inv * siluf_(bflo(gw[0])), o[bb][4 * gq + 1] * inv * siluf_(bfhi(gw[0])));
;                         wv2[e][1] = cvt_pk_bf16(o[bb][4 * gq + 2] * inv * siluf_(bflo(gw[1])), o[bb][4 * gq + 3] * inv * siluf_(bfhi(gw[1]))); }
;                     const auto r0 = __builtin_amdgcn_permlane32_swap(wv2[0][0], wv2[1][0], false, false);
;                     const auto r1 = __builtin_amdgcn_permlane32_swap(wv2[0][1], wv2[1][1], false, false);
;                     u32x4 ov; ov[0] = r0[0]; ov[1] = r1[0]; ov[2] = r0[1]; ov[3] = r1[1];
;                     *(u32x4*)(mixed + (size_t)q2 * DM + head * 128 + 32 * bb + 16 * jp + 8 * h2) = ov;
;                     __builtin_amdgcn_sched_barrier(0);
;                 }
;         }
;     }
	s_nop 0
	v_add_f32_e32 v237, 1.0, v237
	v_rcp_f32_e32 v237, v237
	v_mul_f32_e32 v238, v49, v226
	v_mul_f32_e32 v237, v237, v236
	v_mul_f32_e32 v241, v238, v237
	v_lshlrev_b32_e32 v236, 16, v89
	v_mul_f32_e32 v237, 0xbfb8aa3b, v236
	v_exp_f32_e32 v237, v237
	s_nop 0
	v_add_f32_e32 v237, 1.0, v237
	v_rcp_f32_e32 v237, v237
	v_mul_f32_e32 v238, v50, v226
	v_mul_f32_e32 v237, v237, v236
	v_mul_f32_e32 v242, v238, v237
	v_and_b32_e32 v236, 0xffff0000, v89
	v_mul_f32_e32 v237, 0xbfb8aa3b, v236
	v_exp_f32_e32 v237, v237
	s_nop 0
	v_add_f32_e32 v237, 1.0, v237
	v_rcp_f32_e32 v237, v237
	v_mul_f32_e32 v238, v51, v226
	v_mul_f32_e32 v237, v237, v236
	v_mul_f32_e32 v243, v238, v237
	v_cvt_pk_bf16_f32 v238, v240, v241
	v_cvt_pk_bf16_f32 v239, v242, v243
	global_store_dwordx2 v246, v[238:239], s[20:21] offset:192
	s_nop 1
	v_lshlrev_b32_e32 v236, 16, v90
	v_mul_f32_e32 v237, 0xbfb8aa3b, v236
	v_exp_f32_e32 v237, v237
	s_nop 0
	v_add_f32_e32 v237, 1.0, v237
	v_rcp_f32_e32 v237, v237
	v_mul_f32_e32 v238, v52, v227
	v_mul_f32_e32 v237, v237, v236
	v_mul_f32_e32 v240, v238, v237
	v_and_b32_e32 v236, 0xffff0000, v90
	v_mul_f32_e32 v237, 0xbfb8aa3b, v236
	v_exp_f32_e32 v237, v237
	s_nop 0
	v_add_f32_e32 v237, 1.0, v237
	v_rcp_f32_e32 v237, v237
	v_mul_f32_e32 v238, v53, v227
	v_mul_f32_e32 v237, v237, v236
	v_mul_f32_e32 v241, v238, v237
	v_lshlrev_b32_e32 v236, 16, v91
	v_mul_f32_e32 v237, 0xbfb8aa3b, v236
	v_exp_f32_e32 v237, v237
	s_nop 0
	v_add_f32_e32 v237, 1.0, v237
	v_rcp_f32_e32 v237, v237
	v_mul_f32_e32 v238, v54, v227
	v_mul_f32_e32 v237, v237, v236
	v_mul_f32_e32 v242, v238, v237
	v_and_b32_e32 v236, 0xffff0000, v91
	v_mul_f32_e32 v237, 0xbfb8aa3b, v236
	v_exp_f32_e32 v237, v237
	s_nop 0
	v_add_f32_e32 v237, 1.0, v237
	v_rcp_f32_e32 v237, v237
	v_mul_f32_e32 v238, v55, v227
	v_mul_f32_e32 v237, v237, v236
	v_mul_f32_e32 v243, v238, v237
	v_cvt_pk_bf16_f32 v238, v240, v241
	v_cvt_pk_bf16_f32 v239, v242, v243
	global_store_dwordx2 v247, v[238:239], s[20:21] offset:192
	s_nop 1
	v_lshlrev_b32_e32 v236, 16, v92
	v_mul_f32_e32 v237, 0xbfb8aa3b, v236
	v_exp_f32_e32 v237, v237
	s_nop 0
	v_add_f32_e32 v237, 1.0, v237
	v_rcp_f32_e32 v237, v237
	v_mul_f32_e32 v238, v56, v226
	v_mul_f32_e32 v237, v237, v236
	v_mul_f32_e32 v240, v238, v237
	v_and_b32_e32 v236, 0xffff0000, v92
	v_mul_f32_e32 v237, 0xbfb8aa3b, v236
	v_exp_f32_e32 v237, v237
	s_nop 0
	v_add_f32_e32 v237, 1.0, v237
	v_rcp_f32_e32 v237, v237
	v_mul_f32_e32 v238, v57, v226
	v_mul_f32_e32 v237, v237, v236
	v_mul_f32_e32 v241, v238, v237
	v_lshlrev_b32_e32 v236, 16, v93
	v_mul_f32_e32 v237, 0xbfb8aa3b, v236
	v_exp_f32_e32 v237, v237
	s_nop 0
	v_add_f32_e32 v237, 1.0, v237
	v_rcp_f32_e32 v237, v237
	v_mul_f32_e32 v238, v58, v226
	v_mul_f32_e32 v237, v237, v236
	v_mul_f32_e32 v242, v238, v237
	v_and_b32_e32 v236, 0xffff0000, v93
	v_mul_f32_e32 v237, 0xbfb8aa3b, v236
	v_exp_f32_e32 v237, v237
	s_nop 0
	v_add_f32_e32 v237, 1.0, v237
	v_rcp_f32_e32 v237, v237
	v_mul_f32_e32 v238, v59, v226
	v_mul_f32_e32 v237, v237, v236
	v_mul_f32_e32 v243, v238, v237
	v_cvt_pk_bf16_f32 v238, v240, v241
	v_cvt_pk_bf16_f32 v239, v242, v243
	global_store_dwordx2 v246, v[238:239], s[20:21] offset:224
	s_nop 1
	v_lshlrev_b32_e32 v236, 16, v94
	v_mul_f32_e32 v237, 0xbfb8aa3b, v236
	v_exp_f32_e32 v237, v237
	s_nop 0
	v_add_f32_e32 v237, 1.0, v237
	v_rcp_f32_e32 v237, v237
	v_mul_f32_e32 v238, v60, v227
	v_mul_f32_e32 v237, v237, v236
	v_mul_f32_e32 v240, v238, v237
	v_and_b32_e32 v236, 0xffff0000, v94
	v_mul_f32_e32 v237, 0xbfb8aa3b, v236
	v_exp_f32_e32 v237, v237
	s_nop 0
	v_add_f32_e32 v237, 1.0, v237
	v_rcp_f32_e32 v237, v237
	v_mul_f32_e32 v238, v61, v227
	v_mul_f32_e32 v237, v237, v236
	v_mul_f32_e32 v241, v238, v237
	v_lshlrev_b32_e32 v236, 16, v95
	v_mul_f32_e32 v237, 0xbfb8aa3b, v236
	v_exp_f32_e32 v237, v237
	s_nop 0
	v_add_f32_e32 v237, 1.0, v237
	v_rcp_f32_e32 v237, v237
	v_mul_f32_e32 v238, v62, v227
	v_mul_f32_e32 v237, v237, v236
	v_mul_f32_e32 v242, v238, v237
	v_and_b32_e32 v236, 0xffff0000, v95
	v_mul_f32_e32 v237, 0xbfb8aa3b, v236
	v_exp_f32_e32 v237, v237
	s_nop 0
	v_add_f32_e32 v237, 1.0, v237
	v_rcp_f32_e32 v237, v237
	v_mul_f32_e32 v238, v63, v227
	v_mul_f32_e32 v237, v237, v236
	v_mul_f32_e32 v243, v238, v237
	v_cvt_pk_bf16_f32 v238, v240, v241
	v_cvt_pk_bf16_f32 v239, v242, v243
	global_store_dwordx2 v247, v[238:239], s[20:21] offset:224
	s_nop 1
	s_add_i32 s68, s68, 1
	s_cmp_lt_u32 s68, 2
	s_cbranch_scc1 .La3_unit
	s_add_i32 s55, s55, s57
	s_cmpk_gt_i32 s55, 0xff
	s_cbranch_scc0 .La3_item
	s_branch .LBB0_110
.La3_idle0:
	s_cmp_ge_i32 s22, s17
	s_cbranch_scc1 .La3_nd14
	s_mov_b32 m0, s58
	s_nop 0
	global_load_lds_dwordx4 v202, s[62:63]
.La3_nd14:
	s_cmp_ge_i32 s22, s17
	s_cbranch_scc1 .La3_nd15
	s_add_i32 m0, s58, 0x2000
	s_nop 0
	global_load_lds_dwordx4 v203, s[62:63]
.La3_nd15:
	s_cmp_ge_i32 s22, s17
	s_cbranch_scc1 .La3_nd16
	s_add_i32 m0, s58, 0x4000
	s_nop 0
	global_load_lds_dwordx4 v204, s[62:63]
.La3_nd16:
	s_cmp_ge_i32 s24, s17
	s_cbranch_scc1 .La3_nd17
	s_add_i32 m0, s58, 0x10000
	s_nop 0
	global_load_lds_dwordx4 v205, s[72:73]
.La3_nd17:
	s_cmp_ge_i32 s24, s17
	s_cbranch_scc1 .La3_nd18
	s_add_i32 m0, s58, 0x12000
	s_nop 0
	global_load_lds_dwordx4 v206, s[72:73]

; __device__ __forceinline__ void attn_phase(int wv, const bf16_t* Q, const bf16_t* Kf, const bf16_t* Vt, const bf16_t* proj, bf16_t* mixed, LAS unsigned char* lds) { LIDS
;     ...
;                 asm volatile("s_waitcnt vmcnt(0)" ::: "memory"); __builtin_amdgcn_s_barrier(); asm volatile("" ::: "memory");
;                 if (t + 1 < nt) ATT_ISSUE(t + 1, b ^ 1);
;                 if (64 * t <= qw0 + 31) {
.La3_idle1:
	s_cmp_ge_i32 s22, s17
	s_cbranch_scc1 .La3_nd19
	s_add_i32 m0, s58, 0xa000
	s_nop 0
	global_load_lds_dwordx4 v202, s[62:63]
.La3_nd19:
	s_cmp_ge_i32 s22, s17
	s_cbranch_scc1 .La3_nd20
	s_add_i32 m0, s58, 0xc000
	s_nop 0
	global_load_lds_dwordx4 v203, s[62:63]
.La3_nd20:
	s_cmp_ge_i32 s22, s17
	s_cbranch_scc1 .La3_nd21
	s_add_i32 m0, s58, 0xe000
	s_nop 0
	global_load_lds_dwordx4 v204, s[62:63]
.La3_nd21:
	s_cmp_ge_i32 s24, s17
	s_cbranch_scc1 .La3_nd22
	s_add_i32 m0, s58, 0x6000
	s_nop 0
	global_load_lds_dwordx4 v205, s[72:73]
.La3_nd22:
	s_cmp_ge_i32 s24, s17
	s_cbranch_scc1 .La3_nd23
	s_add_i32 m0, s58, 0x8000
	s_nop 0
	global_load_lds_dwordx4 v206, s[72:73]

; #define ATT_VRD(j) DSR(fr_[(j) & 3], vad[(j) >> 2], ((j) & 3) * 4096)
; __device__ __forceinline__ void attn_phase(int wv, const bf16_t* Q, const bf16_t* Kf, const bf16_t* Vt, const bf16_t* proj, bf16_t* mixed, LAS unsigned char* lds) { LIDS
;     ...
;                 if (t + 1 < nt) ATT_ISSUE(t + 1, b ^ 1);
;     ...
;                     unsigned vad[4];
; #pragma unroll
;                     for (int c = 0; c < 4; ++c) vad[c] = (unsigned)(size_t)vb_ + (unsigned)voffl[c];
;     ...
;                     ATT_VRD(0); ATT_VRD(1); ATT_VRD(2); ATT_VRD(3);
.La3_drain0:
	ds_read_b128 v[178:181], v209 offset:24592
	ds_read_b128 v[182:185], v209 offset:26640
	ds_read_b128 v[186:189], v209 offset:28688
	ds_read_b128 v[190:193], v209 offset:30736
	s_cmp_ge_i32 s22, s17
	s_cbranch_scc1 .La3_nd24
	s_mov_b32 m0, s58
	s_nop 0
	global_load_lds_dwordx4 v202, s[62:63]

; __device__ __forceinline__ unsigned cvt_pk_bf16(float lo, float hi) { unsigned r; asm volatile("v_cvt_pk_bf16_f32 %0, %1, %2" : "=v"(r) : "v"(lo), "v"(hi)); return r; }
; __device__ __forceinline__ float fast_exp2(float x) { return __builtin_amdgcn_exp2f(x); }
; #define LGK(n, f) asm volatile("s_waitcnt lgkmcnt(%1)" : "+v"(f) : "n"(n))
; #define ATT_VRD(j) DSR(fr_[(j) & 3], vad[(j) >> 2], ((j) & 3) * 4096)
; __device__ __forceinline__ void attn_phase(int wv, const bf16_t* Q, const bf16_t* Kf, const bf16_t* Vt, const bf16_t* proj, bf16_t* mixed, LAS unsigned char* lds) { LIDS
;     ...
;                     float ps = 0.f;
; #pragma unroll
;                     for (int kb = 0; kb < 2; ++kb)
; #pragma unroll
;                         for (int j = 0; j < 16; ++j) { s[kb][j] = fast_exp2(s[kb][j] - mrun); ps += s[kb][j]; }
;                     lsum += ps;
; #pragma unroll
;                     for (int c = 0; c < 4; ++c) {
;                         const int kb = c >> 1, sx = c & 1;
;                         u32x4 pw;
; #pragma unroll
;                         for (int j = 0; j < 4; ++j) pw[j] = cvt_pk_bf16(s[kb][8 * sx + 2 * j], s[kb][8 * sx + 2 * j + 1]);
;                         const bf16x8 pf = __builtin_bit_cast(bf16x8, pw);
; #pragma unroll
;                         for (int bb = 0; bb < 4; ++bb) {
;                             const int j = c * 4 + bb;
;                             LGK(j < 13 ? 3 : 15 - j, fr_[j & 3]);
;                             o[bb] = __builtin_amdgcn_mfma_f32_32x32x16_bf16(fr_[j & 3], pf, o[bb], 0, 0, 0);
;                             if (j + 4 < 16) ATT_VRD(j + 4);
;                         }
.La3_nd28:
	s_waitcnt lgkmcnt(3)
	v_exp_f32_e32 v64, v64
	v_exp_f32_e32 v65, v65
	s_nop 0
	v_add_f32_e32 v224, v64, v65
	v_cvt_pk_bf16_f32 v64, v64, v65
	v_exp_f32_e32 v66, v66
	v_exp_f32_e32 v67, v67
	v_add_f32_e32 v224, v224, v66
	v_add_f32_e32 v224, v224, v67
	v_cvt_pk_bf16_f32 v65, v66, v67
	v_exp_f32_e32 v72, v72
	v_exp_f32_e32 v73, v73
	v_add_f32_e32 v224, v224, v72
	v_add_f32_e32 v224, v224, v73
	v_cvt_pk_bf16_f32 v66, v72, v73
	v_exp_f32_e32 v74, v74
	v_exp_f32_e32 v75, v75
	v_add_f32_e32 v224, v224, v74
	v_add_f32_e32 v224, v224, v75
	v_cvt_pk_bf16_f32 v67, v74, v75
	v_exp_f32_e32 v68, v68
	v_exp_f32_e32 v69, v69
	s_nop 0
	v_add_f32_e32 v225, v68, v69
	v_cvt_pk_bf16_f32 v68, v68, v69
	v_exp_f32_e32 v70, v70
	v_exp_f32_e32 v71, v71
	v_add_f32_e32 v225, v225, v70
	v_add_f32_e32 v225, v225, v71
	v_cvt_pk_bf16_f32 v69, v70, v71
	v_exp_f32_e32 v76, v76
	v_exp_f32_e32 v77, v77
	v_add_f32_e32 v225, v225, v76
	v_add_f32_e32 v225, v225, v77
	v_cvt_pk_bf16_f32 v70, v76, v77
	v_exp_f32_e32 v78, v78
	v_exp_f32_e32 v79, v79
	v_add_f32_e32 v225, v225, v78
	v_add_f32_e32 v225, v225, v79
	v_cvt_pk_bf16_f32 v71, v78, v79
	v_mfma_f32_16x16x32_bf16 v[0:3], v[178:181], v[64:67], v[0:3]
	s_nop 0
	v_mfma_f32_16x16x32_bf16 v[4:7], v[178:181], v[68:71], v[4:7]
	ds_read_b128 v[178:181], v209 offset:32784
	v_exp_f32_e32 v80, v80
	v_exp_f32_e32 v81, v81
	v_add_f32_e32 v224, v224, v80
	v_add_f32_e32 v224, v224, v81
	v_cvt_pk_bf16_f32 v80, v80, v81
	v_exp_f32_e32 v82, v82
	s_waitcnt lgkmcnt(3)
	v_mfma_f32_16x16x32_bf16 v[8:11], v[182:185], v[64:67], v[8:11]
	v_mfma_f32_16x16x32_bf16 v[12:15], v[182:185], v[68:71], v[12:15]
	ds_read_b128 v[182:185], v209 offset:34832
	v_exp_f32_e32 v83, v83
	v_add_f32_e32 v224, v224, v82
	v_add_f32_e32 v224, v224, v83
	v_cvt_pk_bf16_f32 v81, v82, v83
	v_exp_f32_e32 v88, v88
	v_exp_f32_e32 v89, v89
	s_waitcnt lgkmcnt(3)
	v_mfma_f32_16x16x32_bf16 v[16:19], v[186:189], v[64:67], v[16:19]
	v_mfma_f32_16x16x32_bf16 v[20:23], v[186:189], v[68:71], v[20:23]
	ds_read_b128 v[186:189], v209 offset:36880
	v_add_f32_e32 v224, v224, v88
	v_add_f32_e32 v224, v224, v89
	v_cvt_pk_bf16_f32 v82, v88, v89
	v_exp_f32_e32 v90, v90
	v_exp_f32_e32 v91, v91
	v_add_f32_e32 v224, v224, v90
	s_waitcnt lgkmcnt(3)
	v_mfma_f32_16x16x32_bf16 v[24:27], v[190:193], v[64:67], v[24:27]
	v_mfma_f32_16x16x32_bf16 v[28:31], v[190:193], v[68:71], v[28:31]
	ds_read_b128 v[190:193], v209 offset:38928
	v_add_f32_e32 v224, v224, v91
	v_cvt_pk_bf16_f32 v83, v90, v91
	v_exp_f32_e32 v84, v84
	v_exp_f32_e32 v85, v85
	v_add_f32_e32 v225, v225, v84
	v_add_f32_e32 v225, v225, v85
	s_waitcnt lgkmcnt(3)
	v_mfma_f32_16x16x32_bf16 v[32:35], v[178:181], v[64:67], v[32:35]
	v_mfma_f32_16x16x32_bf16 v[36:39], v[178:181], v[68:71], v[36:39]
	ds_read_b128 v[178:181], v210 offset:24592
	v_cvt_pk_bf16_f32 v84, v84, v85
	v_exp_f32_e32 v86, v86
	v_exp_f32_e32 v87, v87
	v_add_f32_e32 v225, v225, v86
	v_add_f32_e32 v225, v225, v87
	v_cvt_pk_bf16_f32 v85, v86, v87
	s_waitcnt lgkmcnt(3)
	v_mfma_f32_16x16x32_bf16 v[40:43], v[182:185], v[64:67], v[40:43]
	v_mfma_f32_16x16x32_bf16 v[44:47], v[182:185], v[68:71], v[44:47]
	ds_read_b128 v[182:185], v210 offset:26640
	v_exp_f32_e32 v92, v92
	v_exp_f32_e32 v93, v93
	v_add_f32_e32 v225, v225, v92
	v_add_f32_e32 v225, v225, v93
	v_cvt_pk_bf16_f32 v86, v92, v93
	v_exp_f32_e32 v94, v94
	s_waitcnt lgkmcnt(3)
	v_mfma_f32_16x16x32_bf16 v[48:51], v[186:189], v[64:67], v[48:51]
	v_mfma_f32_16x16x32_bf16 v[52:55], v[186:189], v[68:71], v[52:55]
	ds_read_b128 v[186:189], v210 offset:28688
	v_exp_f32_e32 v95, v95
	v_add_f32_e32 v225, v225, v94
	v_add_f32_e32 v225, v225, v95
	v_cvt_pk_bf16_f32 v87, v94, v95
	v_add_f32_e32 v226, v226, v224
	v_add_f32_e32 v227, v227, v225
	s_waitcnt lgkmcnt(3)
	v_mfma_f32_16x16x32_bf16 v[56:59], v[190:193], v[64:67], v[56:59]
	v_mfma_f32_16x16x32_bf16 v[60:63], v[190:193], v[68:71], v[60:63]
	ds_read_b128 v[190:193], v210 offset:30736
	s_waitcnt lgkmcnt(3)
	v_mfma_f32_16x16x32_bf16 v[0:3], v[178:181], v[80:83], v[0:3]
	v_mfma_f32_16x16x32_bf16 v[4:7], v[178:181], v[84:87], v[4:7]
	ds_read_b128 v[178:181], v210 offset:32784
	s_waitcnt lgkmcnt(3)
	v_mfma_f32_16x16x32_bf16 v[8:11], v[182:185], v[80:83], v[8:11]
	v_mfma_f32_16x16x32_bf16 v[12:15], v[182:185], v[84:87], v[12:15]
	ds_read_b128 v[182:185], v210 offset:34832
	s_waitcnt lgkmcnt(3)
	v_mfma_f32_16x16x32_bf16 v[16:19], v[186:189], v[80:83], v[16:19]
	v_mfma_f32_16x16x32_bf16 v[20:23], v[186:189], v[84:87], v[20:23]
	ds_read_b128 v[186:189], v210 offset:36880
	s_waitcnt lgkmcnt(3)
	v_mfma_f32_16x16x32_bf16 v[24:27], v[190:193], v[80:83], v[24:27]
	v_mfma_f32_16x16x32_bf16 v[28:31], v[190:193], v[84:87], v[28:31]
	ds_read_b128 v[190:193], v210 offset:38928
	s_waitcnt lgkmcnt(3)
	v_mfma_f32_16x16x32_bf16 v[32:35], v[178:181], v[80:83], v[32:35]
	v_mfma_f32_16x16x32_bf16 v[36:39], v[178:181], v[84:87], v[36:39]
	s_waitcnt lgkmcnt(2)
	v_mfma_f32_16x16x32_bf16 v[40:43], v[182:185], v[80:83], v[40:43]
	v_mfma_f32_16x16x32_bf16 v[44:47], v[182:185], v[84:87], v[44:47]
	s_waitcnt lgkmcnt(1)
	v_mfma_f32_16x16x32_bf16 v[48:51], v[186:189], v[80:83], v[48:51]
	v_mfma_f32_16x16x32_bf16 v[52:55], v[186:189], v[84:87], v[52:55]
	s_waitcnt lgkmcnt(0)
	v_mfma_f32_16x16x32_bf16 v[56:59], v[190:193], v[80:83], v[56:59]
	v_mfma_f32_16x16x32_bf16 v[60:63], v[190:193], v[84:87], v[60:63]
	s_branch .La3_tail0
.La3_drain1:
	ds_read_b128 v[178:181], v211 offset:32784
	ds_read_b128 v[182:185], v211 offset:34832
	ds_read_b128 v[186:189], v211 offset:36880
	ds_read_b128 v[190:193], v211 offset:38928
	s_cmp_ge_i32 s22, s17
	s_cbranch_scc1 .La3_nd29
	s_add_i32 m0, s58, 0xa000
	s_nop 0
	global_load_lds_dwordx4 v202, s[62:63]

; __device__ __forceinline__ unsigned cvt_pk_bf16(float lo, float hi) { unsigned r; asm volatile("v_cvt_pk_bf16_f32 %0, %1, %2" : "=v"(r) : "v"(lo), "v"(hi)); return r; }
; __device__ __forceinline__ float fast_exp2(float x) { return __builtin_amdgcn_exp2f(x); }
; #define LGK(n, f) asm volatile("s_waitcnt lgkmcnt(%1)" : "+v"(f) : "n"(n))
; #define ATT_VRD(j) DSR(fr_[(j) & 3], vad[(j) >> 2], ((j) & 3) * 4096)
; __device__ __forceinline__ void attn_phase(int wv, const bf16_t* Q, const bf16_t* Kf, const bf16_t* Vt, const bf16_t* proj, bf16_t* mixed, LAS unsigned char* lds) { LIDS
;     ...
;                     float ps = 0.f;
; #pragma unroll
;                     for (int kb = 0; kb < 2; ++kb)
; #pragma unroll
;                         for (int j = 0; j < 16; ++j) { s[kb][j] = fast_exp2(s[kb][j] - mrun); ps += s[kb][j]; }
;                     lsum += ps;
; #pragma unroll
;                     for (int c = 0; c < 4; ++c) {
;                         const int kb = c >> 1, sx = c & 1;
;                         u32x4 pw;
; #pragma unroll
;                         for (int j = 0; j < 4; ++j) pw[j] = cvt_pk_bf16(s[kb][8 * sx + 2 * j], s[kb][8 * sx + 2 * j + 1]);
;                         const bf16x8 pf = __builtin_bit_cast(bf16x8, pw);
; #pragma unroll
;                         for (int bb = 0; bb < 4; ++bb) {
;                             const int j = c * 4 + bb;
;                             LGK(j < 13 ? 3 : 15 - j, fr_[j & 3]);
;                             o[bb] = __builtin_amdgcn_mfma_f32_32x32x16_bf16(fr_[j & 3], pf, o[bb], 0, 0, 0);
;                             if (j + 4 < 16) ATT_VRD(j + 4);
;                         }
.La3_nd33:
	s_waitcnt lgkmcnt(3)
	v_exp_f32_e32 v96, v96
	v_exp_f32_e32 v97, v97
	s_nop 0
	v_add_f32_e32 v224, v96, v97
	v_cvt_pk_bf16_f32 v96, v96, v97
	v_exp_f32_e32 v98, v98
	v_exp_f32_e32 v99, v99
	v_add_f32_e32 v224, v224, v98
	v_add_f32_e32 v224, v224, v99
	v_cvt_pk_bf16_f32 v97, v98, v99
	v_exp_f32_e32 v104, v104
	v_exp_f32_e32 v105, v105
	v_add_f32_e32 v224, v224, v104
	v_add_f32_e32 v224, v224, v105
	v_cvt_pk_bf16_f32 v98, v104, v105
	v_exp_f32_e32 v106, v106
	v_exp_f32_e32 v107, v107
	v_add_f32_e32 v224, v224, v106
	v_add_f32_e32 v224, v224, v107
	v_cvt_pk_bf16_f32 v99, v106, v107
	v_exp_f32_e32 v100, v100
	v_exp_f32_e32 v101, v101
	s_nop 0
	v_add_f32_e32 v225, v100, v101
	v_cvt_pk_bf16_f32 v100, v100, v101
	v_exp_f32_e32 v102, v102
	v_exp_f32_e32 v103, v103
	v_add_f32_e32 v225, v225, v102
	v_add_f32_e32 v225, v225, v103
	v_cvt_pk_bf16_f32 v101, v102, v103
	v_exp_f32_e32 v108, v108
	v_exp_f32_e32 v109, v109
	v_add_f32_e32 v225, v225, v108
	v_add_f32_e32 v225, v225, v109
	v_cvt_pk_bf16_f32 v102, v108, v109
	v_exp_f32_e32 v110, v110
	v_exp_f32_e32 v111, v111
	v_add_f32_e32 v225, v225, v110
	v_add_f32_e32 v225, v225, v111
	v_cvt_pk_bf16_f32 v103, v110, v111
	v_mfma_f32_16x16x32_bf16 v[0:3], v[178:181], v[96:99], v[0:3]
	s_nop 0
	v_mfma_f32_16x16x32_bf16 v[4:7], v[178:181], v[100:103], v[4:7]
	ds_read_b128 v[178:181], v211 offset:40976
	v_exp_f32_e32 v112, v112
	v_exp_f32_e32 v113, v113
	v_add_f32_e32 v224, v224, v112
	v_add_f32_e32 v224, v224, v113
	v_cvt_pk_bf16_f32 v112, v112, v113
	v_exp_f32_e32 v114, v114
	s_waitcnt lgkmcnt(3)
	v_mfma_f32_16x16x32_bf16 v[8:11], v[182:185], v[96:99], v[8:11]
	v_mfma_f32_16x16x32_bf16 v[12:15], v[182:185], v[100:103], v[12:15]
	ds_read_b128 v[182:185], v211 offset:43024
	v_exp_f32_e32 v115, v115
	v_add_f32_e32 v224, v224, v114
	v_add_f32_e32 v224, v224, v115
	v_cvt_pk_bf16_f32 v113, v114, v115
	v_exp_f32_e32 v120, v120
	v_exp_f32_e32 v121, v121
	s_waitcnt lgkmcnt(3)
	v_mfma_f32_16x16x32_bf16 v[16:19], v[186:189], v[96:99], v[16:19]
	v_mfma_f32_16x16x32_bf16 v[20:23], v[186:189], v[100:103], v[20:23]
	ds_read_b128 v[186:189], v211 offset:45072
	v_add_f32_e32 v224, v224, v120
	v_add_f32_e32 v224, v224, v121
	v_cvt_pk_bf16_f32 v114, v120, v121
	v_exp_f32_e32 v122, v122
	v_exp_f32_e32 v123, v123
	v_add_f32_e32 v224, v224, v122
	s_waitcnt lgkmcnt(3)
	v_mfma_f32_16x16x32_bf16 v[24:27], v[190:193], v[96:99], v[24:27]
	v_mfma_f32_16x16x32_bf16 v[28:31], v[190:193], v[100:103], v[28:31]
	ds_read_b128 v[190:193], v211 offset:47120
	v_add_f32_e32 v224, v224, v123
	v_cvt_pk_bf16_f32 v115, v122, v123
	v_exp_f32_e32 v116, v116
	v_exp_f32_e32 v117, v117
	v_add_f32_e32 v225, v225, v116
	v_add_f32_e32 v225, v225, v117
	s_waitcnt lgkmcnt(3)
	v_mfma_f32_16x16x32_bf16 v[32:35], v[178:181], v[96:99], v[32:35]
	v_mfma_f32_16x16x32_bf16 v[36:39], v[178:181], v[100:103], v[36:39]
	ds_read_b128 v[178:181], v212 offset:32784
	v_cvt_pk_bf16_f32 v116, v116, v117
	v_exp_f32_e32 v118, v118
	v_exp_f32_e32 v119, v119
	v_add_f32_e32 v225, v225, v118
	v_add_f32_e32 v225, v225, v119
	v_cvt_pk_bf16_f32 v117, v118, v119
	s_waitcnt lgkmcnt(3)
	v_mfma_f32_16x16x32_bf16 v[40:43], v[182:185], v[96:99], v[40:43]
	v_mfma_f32_16x16x32_bf16 v[44:47], v[182:185], v[100:103], v[44:47]
	ds_read_b128 v[182:185], v212 offset:34832
	v_exp_f32_e32 v124, v124
	v_exp_f32_e32 v125, v125
	v_add_f32_e32 v225, v225, v124
	v_add_f32_e32 v225, v225, v125
	v_cvt_pk_bf16_f32 v118, v124, v125
	v_exp_f32_e32 v126, v126
	s_waitcnt lgkmcnt(3)
	v_mfma_f32_16x16x32_bf16 v[48:51], v[186:189], v[96:99], v[48:51]
	v_mfma_f32_16x16x32_bf16 v[52:55], v[186:189], v[100:103], v[52:55]
	ds_read_b128 v[186:189], v212 offset:36880
	v_exp_f32_e32 v127, v127
	v_add_f32_e32 v225, v225, v126
	v_add_f32_e32 v225, v225, v127
	v_cvt_pk_bf16_f32 v119, v126, v127
	v_add_f32_e32 v226, v226, v224
	v_add_f32_e32 v227, v227, v225
	s_waitcnt lgkmcnt(3)
	v_mfma_f32_16x16x32_bf16 v[56:59], v[190:193], v[96:99], v[56:59]
	v_mfma_f32_16x16x32_bf16 v[60:63], v[190:193], v[100:103], v[60:63]
	ds_read_b128 v[190:193], v212 offset:38928
	s_waitcnt lgkmcnt(3)
	v_mfma_f32_16x16x32_bf16 v[0:3], v[178:181], v[112:115], v[0:3]
	v_mfma_f32_16x16x32_bf16 v[4:7], v[178:181], v[116:119], v[4:7]
	ds_read_b128 v[178:181], v212 offset:40976
	s_waitcnt lgkmcnt(3)
	v_mfma_f32_16x16x32_bf16 v[8:11], v[182:185], v[112:115], v[8:11]
	v_mfma_f32_16x16x32_bf16 v[12:15], v[182:185], v[116:119], v[12:15]
	ds_read_b128 v[182:185], v212 offset:43024
	s_waitcnt lgkmcnt(3)
	v_mfma_f32_16x16x32_bf16 v[16:19], v[186:189], v[112:115], v[16:19]
	v_mfma_f32_16x16x32_bf16 v[20:23], v[186:189], v[116:119], v[20:23]
	ds_read_b128 v[186:189], v212 offset:45072
	s_waitcnt lgkmcnt(3)
	v_mfma_f32_16x16x32_bf16 v[24:27], v[190:193], v[112:115], v[24:27]
	v_mfma_f32_16x16x32_bf16 v[28:31], v[190:193], v[116:119], v[28:31]
	ds_read_b128 v[190:193], v212 offset:47120
	s_waitcnt lgkmcnt(3)
	v_mfma_f32_16x16x32_bf16 v[32:35], v[178:181], v[112:115], v[32:35]
	v_mfma_f32_16x16x32_bf16 v[36:39], v[178:181], v[116:119], v[36:39]
	s_waitcnt lgkmcnt(2)
	v_mfma_f32_16x16x32_bf16 v[40:43], v[182:185], v[112:115], v[40:43]
	v_mfma_f32_16x16x32_bf16 v[44:47], v[182:185], v[116:119], v[44:47]
	s_waitcnt lgkmcnt(1)
	v_mfma_f32_16x16x32_bf16 v[48:51], v[186:189], v[112:115], v[48:51]
	v_mfma_f32_16x16x32_bf16 v[52:55], v[186:189], v[116:119], v[52:55]
	s_waitcnt lgkmcnt(0)
	v_mfma_f32_16x16x32_bf16 v[56:59], v[190:193], v[112:115], v[56:59]
	v_mfma_f32_16x16x32_bf16 v[60:63], v[190:193], v[116:119], v[60:63]
	s_branch .La3_tail1
; __device__ __forceinline__ float fast_exp2(float x) { return __builtin_amdgcn_exp2f(x); }
; __device__ __forceinline__ void attn_phase(int wv, const bf16_t* Q, const bf16_t* Kf, const bf16_t* Vt, const bf16_t* proj, bf16_t* mixed, LAS unsigned char* lds) { LIDS
;     ...
;                     if (__builtin_amdgcn_ballot_w64(mx > mrun + 8.0f) != 0ull) {
;                         const float mnew = fmaxf(mrun, mx), alpha = fast_exp2(mrun - mnew); mrun = mnew;
;                         lsum *= alpha;
; #pragma unroll
;                         for (int bb = 0; bb < 4; ++bb)
; #pragma unroll
;                             for (int j = 0; j < 16; ++j) o[bb][j] *= alpha;
;                     }
.La3_rare0:
	s_nop 9
	v_sub_f32_e32 v221, v218, v194
	v_max_f32_e32 v222, v228, v221
	v_sub_f32_e32 v221, v228, v222
	v_exp_f32_e32 v221, v221
	v_add_f32_e32 v223, v222, v194
	v_mov_b32_e32 v228, v222
	v_sub_f32_e32 v96, v96, v223
	v_sub_f32_e32 v97, v97, v223
	v_sub_f32_e32 v98, v98, v223
	v_sub_f32_e32 v99, v99, v223
	v_sub_f32_e32 v104, v104, v223
	v_sub_f32_e32 v105, v105, v223
	v_sub_f32_e32 v106, v106, v223
	v_sub_f32_e32 v107, v107, v223
	v_sub_f32_e32 v112, v112, v223
	v_sub_f32_e32 v113, v113, v223
	v_sub_f32_e32 v114, v114, v223
	v_sub_f32_e32 v115, v115, v223
	v_sub_f32_e32 v120, v120, v223
	v_sub_f32_e32 v121, v121, v223
	v_sub_f32_e32 v122, v122, v223
	v_sub_f32_e32 v123, v123, v223
	v_sub_f32_e32 v194, 0, v222
	v_mov_b32_e32 v195, v194
	v_mov_b32_e32 v196, v194
	v_mov_b32_e32 v197, v194
	v_mul_f32_e32 v0, v221, v0
	v_mul_f32_e32 v1, v221, v1
	v_mul_f32_e32 v2, v221, v2
	v_mul_f32_e32 v3, v221, v3
	v_mul_f32_e32 v8, v221, v8
	v_mul_f32_e32 v9, v221, v9
	v_mul_f32_e32 v10, v221, v10
	v_mul_f32_e32 v11, v221, v11
	v_mul_f32_e32 v16, v221, v16
	v_mul_f32_e32 v17, v221, v17
	v_mul_f32_e32 v18, v221, v18
	v_mul_f32_e32 v19, v221, v19
	v_mul_f32_e32 v24, v221, v24
	v_mul_f32_e32 v25, v221, v25
	v_mul_f32_e32 v26, v221, v26
	v_mul_f32_e32 v27, v221, v27
	v_mul_f32_e32 v32, v221, v32
	v_mul_f32_e32 v33, v221, v33
	v_mul_f32_e32 v34, v221, v34
	v_mul_f32_e32 v35, v221, v35
	v_mul_f32_e32 v40, v221, v40
	v_mul_f32_e32 v41, v221, v41
	v_mul_f32_e32 v42, v221, v42
	v_mul_f32_e32 v43, v221, v43
	v_mul_f32_e32 v48, v221, v48
	v_mul_f32_e32 v49, v221, v49
	v_mul_f32_e32 v50, v221, v50
	v_mul_f32_e32 v51, v221, v51
	v_mul_f32_e32 v56, v221, v56
	v_mul_f32_e32 v57, v221, v57
	v_mul_f32_e32 v58, v221, v58
	v_mul_f32_e32 v59, v221, v59
	v_mul_f32_e32 v226, v221, v226
	v_sub_f32_e32 v221, v219, v198
	v_max_f32_e32 v222, v229, v221
	v_sub_f32_e32 v221, v229, v222
	v_exp_f32_e32 v221, v221
	v_add_f32_e32 v223, v222, v198
	v_mov_b32_e32 v229, v222
	v_sub_f32_e32 v100, v100, v223
	v_sub_f32_e32 v101, v101, v223
	v_sub_f32_e32 v102, v102, v223
	v_sub_f32_e32 v103, v103, v223
	v_sub_f32_e32 v108, v108, v223
	v_sub_f32_e32 v109, v109, v223
	v_sub_f32_e32 v110, v110, v223
	v_sub_f32_e32 v111, v111, v223
	v_sub_f32_e32 v116, v116, v223
	v_sub_f32_e32 v117, v117, v223
	v_sub_f32_e32 v118, v118, v223
	v_sub_f32_e32 v119, v119, v223
	v_sub_f32_e32 v124, v124, v223
	v_sub_f32_e32 v125, v125, v223
	v_sub_f32_e32 v126, v126, v223
	v_sub_f32_e32 v127, v127, v223
	v_sub_f32_e32 v198, 0, v222
	v_mov_b32_e32 v199, v198
	v_mov_b32_e32 v200, v198
	v_mov_b32_e32 v201, v198
	v_mul_f32_e32 v4, v221, v4
	v_mul_f32_e32 v5, v221, v5
	v_mul_f32_e32 v6, v221, v6
	v_mul_f32_e32 v7, v221, v7
	v_mul_f32_e32 v12, v221, v12
	v_mul_f32_e32 v13, v221, v13
	v_mul_f32_e32 v14, v221, v14
	v_mul_f32_e32 v15, v221, v15
	v_mul_f32_e32 v20, v221, v20
	v_mul_f32_e32 v21, v221, v21
	v_mul_f32_e32 v22, v221, v22
	v_mul_f32_e32 v23, v221, v23
	v_mul_f32_e32 v28, v221, v28
	v_mul_f32_e32 v29, v221, v29
	v_mul_f32_e32 v30, v221, v30
	v_mul_f32_e32 v31, v221, v31
	v_mul_f32_e32 v36, v221, v36
	v_mul_f32_e32 v37, v221, v37
	v_mul_f32_e32 v38, v221, v38
	v_mul_f32_e32 v39, v221, v39
	v_mul_f32_e32 v44, v221, v44
	v_mul_f32_e32 v45, v221, v45
	v_mul_f32_e32 v46, v221, v46
	v_mul_f32_e32 v47, v221, v47
	v_mul_f32_e32 v52, v221, v52
	v_mul_f32_e32 v53, v221, v53
	v_mul_f32_e32 v54, v221, v54
	v_mul_f32_e32 v55, v221, v55
	v_mul_f32_e32 v60, v221, v60
	v_mul_f32_e32 v61, v221, v61
	v_mul_f32_e32 v62, v221, v62
	v_mul_f32_e32 v63, v221, v63
	v_mul_f32_e32 v227, v221, v227
	v_mov_b32_e32 v230, 0x41000000
	s_branch .La3_tail0
; __device__ __forceinline__ float fast_exp2(float x) { return __builtin_amdgcn_exp2f(x); }
; __device__ __forceinline__ void attn_phase(int wv, const bf16_t* Q, const bf16_t* Kf, const bf16_t* Vt, const bf16_t* proj, bf16_t* mixed, LAS unsigned char* lds) { LIDS
;     ...
;                     if (__builtin_amdgcn_ballot_w64(mx > mrun + 8.0f) != 0ull) {
;                         const float mnew = fmaxf(mrun, mx), alpha = fast_exp2(mrun - mnew); mrun = mnew;
;                         lsum *= alpha;
; #pragma unroll
;                         for (int bb = 0; bb < 4; ++bb)
; #pragma unroll
;                             for (int j = 0; j < 16; ++j) o[bb][j] *= alpha;
;                     }
.La3_rare1:
	s_nop 9
	v_sub_f32_e32 v221, v218, v194
	v_max_f32_e32 v222, v228, v221
	v_sub_f32_e32 v221, v228, v222
	v_exp_f32_e32 v221, v221
	v_add_f32_e32 v223, v222, v194
	v_mov_b32_e32 v228, v222
	v_sub_f32_e32 v64, v64, v223
	v_sub_f32_e32 v65, v65, v223
	v_sub_f32_e32 v66, v66, v223
	v_sub_f32_e32 v67, v67, v223
	v_sub_f32_e32 v72, v72, v223
	v_sub_f32_e32 v73, v73, v223
	v_sub_f32_e32 v74, v74, v223
	v_sub_f32_e32 v75, v75, v223
	v_sub_f32_e32 v80, v80, v223
	v_sub_f32_e32 v81, v81, v223
	v_sub_f32_e32 v82, v82, v223
	v_sub_f32_e32 v83, v83, v223
	v_sub_f32_e32 v88, v88, v223
	v_sub_f32_e32 v89, v89, v223
	v_sub_f32_e32 v90, v90, v223
	v_sub_f32_e32 v91, v91, v223
	v_sub_f32_e32 v194, 0, v222
	v_mov_b32_e32 v195, v194
	v_mov_b32_e32 v196, v194
	v_mov_b32_e32 v197, v194
	v_mul_f32_e32 v0, v221, v0
	v_mul_f32_e32 v1, v221, v1
	v_mul_f32_e32 v2, v221, v2
	v_mul_f32_e32 v3, v221, v3
	v_mul_f32_e32 v8, v221, v8
	v_mul_f32_e32 v9, v221, v9
	v_mul_f32_e32 v10, v221, v10
	v_mul_f32_e32 v11, v221, v11
	v_mul_f32_e32 v16, v221, v16
	v_mul_f32_e32 v17, v221, v17
	v_mul_f32_e32 v18, v221, v18
	v_mul_f32_e32 v19, v221, v19
	v_mul_f32_e32 v24, v221, v24
	v_mul_f32_e32 v25, v221, v25
	v_mul_f32_e32 v26, v221, v26
	v_mul_f32_e32 v27, v221, v27
	v_mul_f32_e32 v32, v221, v32
	v_mul_f32_e32 v33, v221, v33
	v_mul_f32_e32 v34, v221, v34
	v_mul_f32_e32 v35, v221, v35
	v_mul_f32_e32 v40, v221, v40
	v_mul_f32_e32 v41, v221, v41
	v_mul_f32_e32 v42, v221, v42
	v_mul_f32_e32 v43, v221, v43
	v_mul_f32_e32 v48, v221, v48
	v_mul_f32_e32 v49, v221, v49
	v_mul_f32_e32 v50, v221, v50
	v_mul_f32_e32 v51, v221, v51
	v_mul_f32_e32 v56, v221, v56
	v_mul_f32_e32 v57, v221, v57
	v_mul_f32_e32 v58, v221, v58
	v_mul_f32_e32 v59, v221, v59
	v_mul_f32_e32 v226, v221, v226
	v_sub_f32_e32 v221, v219, v198
	v_max_f32_e32 v222, v229, v221
	v_sub_f32_e32 v221, v229, v222
	v_exp_f32_e32 v221, v221
	v_add_f32_e32 v223, v222, v198
	v_mov_b32_e32 v229, v222
	v_sub_f32_e32 v68, v68, v223
	v_sub_f32_e32 v69, v69, v223
	v_sub_f32_e32 v70, v70, v223
	v_sub_f32_e32 v71, v71, v223
	v_sub_f32_e32 v76, v76, v223
	v_sub_f32_e32 v77, v77, v223
	v_sub_f32_e32 v78, v78, v223
	v_sub_f32_e32 v79, v79, v223
	v_sub_f32_e32 v84, v84, v223
	v_sub_f32_e32 v85, v85, v223
	v_sub_f32_e32 v86, v86, v223
	v_sub_f32_e32 v87, v87, v223
	v_sub_f32_e32 v92, v92, v223
	v_sub_f32_e32 v93, v93, v223
	v_sub_f32_e32 v94, v94, v223
	v_sub_f32_e32 v95, v95, v223
	v_sub_f32_e32 v198, 0, v222
	v_mov_b32_e32 v199, v198
	v_mov_b32_e32 v200, v198
	v_mov_b32_e32 v201, v198
	v_mul_f32_e32 v4, v221, v4
	v_mul_f32_e32 v5, v221, v5
	v_mul_f32_e32 v6, v221, v6
	v_mul_f32_e32 v7, v221, v7
	v_mul_f32_e32 v12, v221, v12
	v_mul_f32_e32 v13, v221, v13
	v_mul_f32_e32 v14, v221, v14
	v_mul_f32_e32 v15, v221, v15
	v_mul_f32_e32 v20, v221, v20
	v_mul_f32_e32 v21, v221, v21
	v_mul_f32_e32 v22, v221, v22
	v_mul_f32_e32 v23, v221, v23
	v_mul_f32_e32 v28, v221, v28
	v_mul_f32_e32 v29, v221, v29
	v_mul_f32_e32 v30, v221, v30
	v_mul_f32_e32 v31, v221, v31
	v_mul_f32_e32 v36, v221, v36
	v_mul_f32_e32 v37, v221, v37
	v_mul_f32_e32 v38, v221, v38
	v_mul_f32_e32 v39, v221, v39
	v_mul_f32_e32 v44, v221, v44
	v_mul_f32_e32 v45, v221, v45
	v_mul_f32_e32 v46, v221, v46
	v_mul_f32_e32 v47, v221, v47
	v_mul_f32_e32 v52, v221, v52
	v_mul_f32_e32 v53, v221, v53
	v_mul_f32_e32 v54, v221, v54
	v_mul_f32_e32 v55, v221, v55
	v_mul_f32_e32 v60, v221, v60
	v_mul_f32_e32 v61, v221, v61
	v_mul_f32_e32 v62, v221, v62
	v_mul_f32_e32 v63, v221, v63
	v_mul_f32_e32 v227, v221, v227
	v_mov_b32_e32 v230, 0x41000000
	s_branch .La3_tail1
